# grid barrier acquire: wave 1 performs the L1 invalidate (and waits for it) right after the entry s_barrier, in parallel with lane 0's arrival protocol, instead of lane 0 doing it after the wait
# baseline (speedup 1.0000x reference)
; __device__ __forceinline__ void xcd_barrier(const XcdBarrier& b) {
;     asm volatile("s_waitcnt vmcnt(0)" ::: "memory");
;     __syncthreads();
;     if (threadIdx.x == 0) {
;         unsigned* bar = b.bar;
;         __builtin_amdgcn_s_waitcnt(0);
;         unsigned nloc = b.st[0], nx = b.st[1];
;         if (nloc == 0u) { xcd_barrier_complete(bar, b.x, nloc, nx); b.st[0] = nloc; b.st[1] = nx; }
.LBB0_59:
	s_waitcnt vmcnt(0)
	s_waitcnt lgkmcnt(0)
	s_barrier
	v_readfirstlane_b32 s0, v212
	s_cmp_lg_u32 s0, 64
	s_cbranch_scc1 .Linv_0
	buffer_inv sc1
	s_waitcnt vmcnt(0)
.Linv_0:
	s_mov_b64 s[0:1], exec
	v_readlane_b32 s4, v248, 6
	v_readlane_b32 s5, v248, 7
	s_and_b64 s[4:5], s[0:1], s[4:5]
	s_mov_b64 exec, s[4:5]
	s_cbranch_execz .LBB0_111
	s_add_i32 s4, 0, 0x20020
	v_mov_b32_e32 v0, s4
	s_waitcnt vmcnt(0) expcnt(0) lgkmcnt(0)
	ds_read_b32 v2, v0
	s_add_i32 s4, 0, 0x20024
	v_mov_b32_e32 v0, s4
	ds_read_b32 v0, v0
	s_waitcnt lgkmcnt(1)
	v_cmp_ne_u32_e32 vcc, 0, v2
	s_cbranch_vccnz .LBB0_75
	v_readlane_b32 s4, v248, 2
	v_readlane_b32 s5, v248, 3
	v_readlane_b32 s6, v248, 1
	s_mul_i32 s18, s5, s6
	s_mul_i32 s18, s18, s4
	s_add_u32 s4, s94, 0x40200
	s_addc_u32 s5, s95, 0
	s_add_u32 s6, s94, 0x40400
	s_addc_u32 s7, s95, 0
	s_add_u32 s8, s94, 0x40500
	s_addc_u32 s9, s95, 0
	s_add_u32 s10, s94, 0x40600
	s_addc_u32 s11, s95, 0
	s_add_u32 s36, s94, 0x40700
	s_addc_u32 s37, s95, 0
	s_add_u32 s40, s94, 0x40800
	s_addc_u32 s41, s95, 0
	s_add_u32 s44, s94, 0x40900
	s_addc_u32 s45, s95, 0
	s_add_u32 s46, s94, 0x40a00
	s_addc_u32 s47, s95, 0
	s_add_u32 s48, s94, 0x40b00
	s_addc_u32 s49, s95, 0
	s_add_u32 s50, s94, 0x40c00
	s_addc_u32 s51, s95, 0
	s_add_u32 s52, s94, 0x40d00
	s_addc_u32 s53, s95, 0
	s_add_u32 s54, s94, 0x40e00
	s_addc_u32 s55, s95, 0
	s_add_u32 s56, s94, 0x40f00
	s_addc_u32 s57, s95, 0
	s_add_u32 s60, s94, 0x41000
	s_addc_u32 s61, s95, 0
	s_add_u32 s72, s94, 0x41100
	s_addc_u32 s73, s95, 0
	s_add_u32 s74, s94, 0x41200
	s_addc_u32 s75, s95, 0
	s_add_u32 s34, s94, 0x41300
	s_addc_u32 s35, s95, 0
	s_mov_b32 s19, 1
	v_mov_b32_e32 v16, 0
	s_branch .LBB0_63

; __device__ __forceinline__ unsigned xb_ld(unsigned* p)              { return __hip_atomic_load(p, __ATOMIC_RELAXED, __HIP_MEMORY_SCOPE_AGENT); }
; #define XB_SPIN(cond, bar) do { unsigned _sp = 0; while (cond) { __builtin_amdgcn_s_sleep(1); \
;     if ((++_sp & 255u) == 0u) { if (xb_ld(&(bar)[XB_TMO])) break; if (_sp > XB_SPIN_CAP) { atomicAdd(&(bar)[XB_TMO], 1u); break; } } } } while (0)
; __device__ __forceinline__ void xcd_barrier(const XcdBarrier& b) {
;     ...
;             XB_SPIN(xb_ld(&bar[XB_XGEN(b.x)]) == gen, bar);
;             __builtin_amdgcn_fence(__ATOMIC_ACQUIRE, "agent");
;             asm volatile("s_waitcnt vmcnt(0)" ::: "memory");
.LBB0_90:
	s_or_b64 exec, exec, s[8:9]
	s_waitcnt vmcnt(0)
	s_waitcnt vmcnt(0)

; __device__ __forceinline__ unsigned xb_add(unsigned* p, unsigned v) { return __hip_atomic_fetch_add(p, v, __ATOMIC_RELAXED, __HIP_MEMORY_SCOPE_AGENT); }
; __device__ __forceinline__ void xcd_barrier(const XcdBarrier& b) {
;     ...
;             __builtin_amdgcn_fence(__ATOMIC_ACQUIRE, "agent");
;             xb_add(&bar[XB_XGEN(b.x)], 1u);
;             asm volatile("s_waitcnt vmcnt(0)" ::: "memory");
.LBB0_108:
	s_or_b64 exec, exec, s[6:7]
	s_mov_b64 s[6:7], exec
	v_mbcnt_lo_u32_b32 v0, s6, 0
	v_mbcnt_hi_u32_b32 v0, s7, v0
	v_cmp_eq_u32_e32 vcc, 0, v0
	s_waitcnt vmcnt(0)
	s_and_saveexec_b64 s[8:9], vcc
	s_cbranch_execz .LBB0_110
	s_bcnt1_i32_b64 s6, s[6:7]

; __device__ __forceinline__ void xcd_barrier(const XcdBarrier& b) {
;     asm volatile("s_waitcnt vmcnt(0)" ::: "memory");
;     __syncthreads();
;     if (threadIdx.x == 0) {
;         unsigned* bar = b.bar;
;         __builtin_amdgcn_s_waitcnt(0);
;         unsigned nloc = b.st[0], nx = b.st[1];
;         if (nloc == 0u) { xcd_barrier_complete(bar, b.x, nloc, nx); b.st[0] = nloc; b.st[1] = nx; }
.LBB0_342:
	s_waitcnt vmcnt(0)
	s_barrier
	s_waitcnt vmcnt(0)
	s_waitcnt vmcnt(0)
	s_barrier
	v_readfirstlane_b32 s0, v212
	s_cmp_lg_u32 s0, 64
	s_cbranch_scc1 .Linv_1
	buffer_inv sc1
	s_waitcnt vmcnt(0)
.Linv_1:
	s_mov_b64 s[0:1], exec
	v_readlane_b32 s4, v248, 6
	v_readlane_b32 s5, v248, 7
	s_and_b64 s[4:5], s[0:1], s[4:5]
	v_readlane_b32 s80, v248, 11
	s_xor_b64 s[0:1], s[4:5], s[0:1]
	v_readlane_b32 s81, v248, 12
	v_readlane_b32 s82, v248, 13
	v_readlane_b32 s83, v248, 14
	v_readlane_b32 s84, v248, 15
	v_readlane_b32 s85, v248, 16
	v_readlane_b32 s86, v248, 17
	v_readlane_b32 s87, v248, 18
	v_readlane_b32 s88, v248, 19
	v_readlane_b32 s89, v248, 20
	v_readlane_b32 s90, v248, 21
	v_readlane_b32 s91, v248, 22
	v_readlane_b32 s92, v248, 23
	v_readlane_b32 s93, v248, 24
	v_readlane_b32 s94, v248, 25
	v_readlane_b32 s95, v248, 26
	v_readlane_b32 s24, v248, 9
	s_mov_b64 exec, s[4:5]
	s_cbranch_execz .LBB0_395
	s_add_i32 s4, 0, 0x20020
	v_mov_b32_e32 v0, s4
	s_waitcnt vmcnt(0) expcnt(0) lgkmcnt(0)
	ds_read_b32 v2, v0
	s_add_i32 s4, 0, 0x20024
	v_mov_b32_e32 v0, s4
	ds_read_b32 v0, v0
	s_waitcnt lgkmcnt(1)
	v_cmp_ne_u32_e32 vcc, 0, v2
	s_cbranch_vccnz .LBB0_358
	v_readlane_b32 s4, v248, 2
	v_readlane_b32 s5, v248, 3
	v_readlane_b32 s6, v248, 1
	s_mul_i32 s18, s5, s6
	s_mul_i32 s18, s18, s4
	s_add_u32 s4, s94, 0x40200
	s_addc_u32 s5, s95, 0
	s_add_u32 s6, s94, 0x40400
	s_addc_u32 s7, s95, 0
	s_add_u32 s8, s94, 0x40500
	s_addc_u32 s9, s95, 0
	s_add_u32 s10, s94, 0x40600
	s_addc_u32 s11, s95, 0
	s_add_u32 s58, s94, 0x40700
	s_addc_u32 s59, s95, 0
	s_add_u32 s78, s94, 0x40800
	s_addc_u32 s79, s95, 0
	s_add_u32 s22, s94, 0x40900
	s_addc_u32 s23, s95, 0
	s_add_u32 s28, s94, 0x40a00
	s_addc_u32 s29, s95, 0
	s_add_u32 s30, s94, 0x40b00
	s_addc_u32 s31, s95, 0
	s_add_u32 s76, s94, 0x40c00
	s_addc_u32 s77, s95, 0
	s_add_u32 s80, s94, 0x40d00
	s_addc_u32 s81, s95, 0
	s_add_u32 s82, s94, 0x40e00
	s_addc_u32 s83, s95, 0
	s_add_u32 s84, s94, 0x40f00
	s_addc_u32 s85, s95, 0
	s_add_u32 s86, s94, 0x41000
	s_addc_u32 s87, s95, 0
	s_add_u32 s96, s94, 0x41100
	s_addc_u32 s97, s95, 0
	s_add_u32 s34, s94, 0x41200
	s_addc_u32 s35, s95, 0
	s_add_u32 s48, s94, 0x41300
	s_addc_u32 s49, s95, 0
	s_mov_b32 s19, 1
	v_mov_b32_e32 v16, 0
	s_branch .LBB0_346

; __device__ __forceinline__ unsigned xb_add(unsigned* p, unsigned v) { return __hip_atomic_fetch_add(p, v, __ATOMIC_RELAXED, __HIP_MEMORY_SCOPE_AGENT); }
; __device__ __forceinline__ void xcd_barrier(const XcdBarrier& b) {
;     ...
;             __builtin_amdgcn_fence(__ATOMIC_ACQUIRE, "agent");
;             xb_add(&bar[XB_XGEN(b.x)], 1u);
;             asm volatile("s_waitcnt vmcnt(0)" ::: "memory");
.LBB0_391:
	s_or_b64 exec, exec, s[8:9]
	s_mov_b64 s[8:9], exec
	v_mbcnt_lo_u32_b32 v0, s8, 0
	v_mbcnt_hi_u32_b32 v0, s9, v0
	v_cmp_eq_u32_e32 vcc, 0, v0
	s_waitcnt vmcnt(0)
	s_and_saveexec_b64 s[10:11], vcc
	s_cbranch_execz .LBB0_393
	s_bcnt1_i32_b64 s8, s[8:9]

; __device__ __forceinline__ void xcd_barrier(const XcdBarrier& b) {
;     asm volatile("s_waitcnt vmcnt(0)" ::: "memory");
;     __syncthreads();
;     if (threadIdx.x == 0) {
;         unsigned* bar = b.bar;
;         __builtin_amdgcn_s_waitcnt(0);
;         unsigned nloc = b.st[0], nx = b.st[1];
;         if (nloc == 0u) { xcd_barrier_complete(bar, b.x, nloc, nx); b.st[0] = nloc; b.st[1] = nx; }
.LBB0_465:
	s_or_b64 exec, exec, s[6:7]
	s_waitcnt vmcnt(0)
	s_barrier
	v_readfirstlane_b32 s0, v212
	s_cmp_lg_u32 s0, 64
	s_cbranch_scc1 .Linv_2
	buffer_inv sc1
	s_waitcnt vmcnt(0)
.Linv_2:
	s_mov_b64 s[0:1], exec
	v_readlane_b32 s4, v248, 6
	v_readlane_b32 s5, v248, 7
	s_and_b64 s[4:5], s[0:1], s[4:5]
	s_mov_b64 exec, s[4:5]
	s_cbranch_execz .LBB0_518
	s_add_i32 s4, 0, 0x20020
	v_mov_b32_e32 v0, s4
	s_waitcnt vmcnt(0) expcnt(0) lgkmcnt(0)
	ds_read_b32 v2, v0
	s_add_i32 s4, 0, 0x20024
	v_mov_b32_e32 v0, s4
	ds_read_b32 v0, v0
	s_waitcnt lgkmcnt(1)
	v_cmp_ne_u32_e32 vcc, 0, v2
	s_cbranch_vccnz .LBB0_481
	v_readlane_b32 s4, v248, 2
	v_readlane_b32 s5, v248, 3
	v_readlane_b32 s6, v248, 1
	s_mul_i32 s18, s5, s6
	s_mul_i32 s18, s18, s4
	s_add_u32 s4, s94, 0x40200
	s_addc_u32 s5, s95, 0
	s_add_u32 s6, s94, 0x40400
	s_addc_u32 s7, s95, 0
	s_add_u32 s8, s94, 0x40500
	s_addc_u32 s9, s95, 0
	s_add_u32 s10, s94, 0x40600
	s_addc_u32 s11, s95, 0
	s_add_u32 s56, s94, 0x40700
	s_addc_u32 s57, s95, 0
	s_add_u32 s58, s94, 0x40800
	s_addc_u32 s59, s95, 0
	s_add_u32 s60, s94, 0x40900
	s_addc_u32 s61, s95, 0
	s_add_u32 s64, s94, 0x40a00
	s_addc_u32 s65, s95, 0
	s_add_u32 s66, s94, 0x40b00
	s_addc_u32 s67, s95, 0
	s_add_u32 s72, s94, 0x40c00
	s_addc_u32 s73, s95, 0
	s_add_u32 s74, s94, 0x40d00
	s_addc_u32 s75, s95, 0
	s_add_u32 s76, s94, 0x40e00
	s_addc_u32 s77, s95, 0
	s_add_u32 s78, s94, 0x40f00
	s_addc_u32 s79, s95, 0
	s_add_u32 s80, s94, 0x41000
	s_addc_u32 s81, s95, 0
	s_add_u32 s82, s94, 0x41100
	s_addc_u32 s83, s95, 0
	s_add_u32 s34, s94, 0x41200
	s_addc_u32 s35, s95, 0
	s_add_u32 s48, s94, 0x41300
	s_addc_u32 s49, s95, 0
	s_mov_b32 s19, 1
	v_mov_b32_e32 v16, 0
	s_branch .LBB0_469

; __device__ __forceinline__ void xcd_barrier(const XcdBarrier& b) {
;     asm volatile("s_waitcnt vmcnt(0)" ::: "memory");
;     __syncthreads();
;     if (threadIdx.x == 0) {
;         unsigned* bar = b.bar;
;         __builtin_amdgcn_s_waitcnt(0);
;         unsigned nloc = b.st[0], nx = b.st[1];
;         if (nloc == 0u) { xcd_barrier_complete(bar, b.x, nloc, nx); b.st[0] = nloc; b.st[1] = nx; }
.LBB0_560:
	s_waitcnt vmcnt(0)
	s_barrier
	v_readfirstlane_b32 s0, v212
	s_cmp_lg_u32 s0, 64
	s_cbranch_scc1 .Linv_3
	buffer_inv sc1
	s_waitcnt vmcnt(0)
.Linv_3:
	s_mov_b64 s[0:1], exec
	v_readlane_b32 s4, v248, 6
	v_readlane_b32 s5, v248, 7
	s_and_b64 s[4:5], s[0:1], s[4:5]
	s_xor_b64 s[0:1], s[4:5], s[0:1]
	s_mov_b64 exec, s[4:5]
	s_cbranch_execz .LBB0_613
	s_add_i32 s4, 0, 0x20020
	v_mov_b32_e32 v0, s4
	s_waitcnt vmcnt(0) expcnt(0) lgkmcnt(0)
	ds_read_b32 v2, v0
	s_add_i32 s4, 0, 0x20024
	v_mov_b32_e32 v0, s4
	ds_read_b32 v0, v0
	s_waitcnt lgkmcnt(1)
	v_cmp_ne_u32_e32 vcc, 0, v2
	s_cbranch_vccnz .LBB0_576
	v_readlane_b32 s4, v248, 2
	v_readlane_b32 s5, v248, 3
	v_readlane_b32 s8, v248, 1
	s_mul_i32 s18, s5, s8
	s_mul_i32 s18, s18, s4
	s_add_u32 s4, s94, 0x40200
	s_addc_u32 s5, s95, 0
	s_add_u32 s8, s94, 0x40400
	s_addc_u32 s9, s95, 0
	s_add_u32 s10, s94, 0x40500
	s_addc_u32 s11, s95, 0
	s_add_u32 s38, s94, 0x40600
	s_addc_u32 s39, s95, 0
	s_add_u32 s42, s94, 0x40700
	s_addc_u32 s43, s95, 0
	s_add_u32 s54, s94, 0x40800
	s_addc_u32 s55, s95, 0
	s_add_u32 s56, s94, 0x40900
	s_addc_u32 s57, s95, 0
	s_add_u32 s58, s94, 0x40a00
	s_addc_u32 s59, s95, 0
	s_add_u32 s60, s94, 0x40b00
	s_addc_u32 s61, s95, 0
	s_add_u32 s62, s94, 0x40c00
	s_addc_u32 s63, s95, 0
	s_add_u32 s64, s94, 0x40d00
	s_addc_u32 s65, s95, 0
	s_add_u32 s66, s94, 0x40e00
	s_addc_u32 s67, s95, 0
	s_add_u32 s70, s94, 0x40f00
	s_addc_u32 s71, s95, 0
	s_add_u32 s72, s94, 0x41000
	s_addc_u32 s73, s95, 0
	s_add_u32 s74, s94, 0x41100
	s_addc_u32 s75, s95, 0
	s_add_u32 s34, s94, 0x41200
	s_addc_u32 s35, s95, 0
	s_add_u32 s48, s94, 0x41300
	s_addc_u32 s49, s95, 0
	s_mov_b32 s19, 1
	v_mov_b32_e32 v16, 0
	s_branch .LBB0_564

; __device__ __forceinline__ unsigned xb_ld(unsigned* p)              { return __hip_atomic_load(p, __ATOMIC_RELAXED, __HIP_MEMORY_SCOPE_AGENT); }
; #define XB_SPIN(cond, bar) do { unsigned _sp = 0; while (cond) { __builtin_amdgcn_s_sleep(1); \
;     if ((++_sp & 255u) == 0u) { if (xb_ld(&(bar)[XB_TMO])) break; if (_sp > XB_SPIN_CAP) { atomicAdd(&(bar)[XB_TMO], 1u); break; } } } } while (0)
; __device__ __forceinline__ void xcd_barrier(const XcdBarrier& b) {
;     ...
;             XB_SPIN(xb_ld(&bar[XB_XGEN(b.x)]) == gen, bar);
;             __builtin_amdgcn_fence(__ATOMIC_ACQUIRE, "agent");
;             asm volatile("s_waitcnt vmcnt(0)" ::: "memory");
.LBB0_591:
	s_or_b64 exec, exec, s[10:11]
	s_waitcnt vmcnt(0)
	s_waitcnt vmcnt(0)

; __device__ __forceinline__ unsigned xb_add(unsigned* p, unsigned v) { return __hip_atomic_fetch_add(p, v, __ATOMIC_RELAXED, __HIP_MEMORY_SCOPE_AGENT); }
; __device__ __forceinline__ void xcd_barrier(const XcdBarrier& b) {
;     ...
;             __builtin_amdgcn_fence(__ATOMIC_ACQUIRE, "agent");
;             xb_add(&bar[XB_XGEN(b.x)], 1u);
;             asm volatile("s_waitcnt vmcnt(0)" ::: "memory");
.LBB0_609:
	s_or_b64 exec, exec, s[10:11]
	s_mov_b64 s[10:11], exec
	v_mbcnt_lo_u32_b32 v0, s10, 0
	v_mbcnt_hi_u32_b32 v0, s11, v0
	v_cmp_eq_u32_e32 vcc, 0, v0
	s_waitcnt vmcnt(0)
	s_and_saveexec_b64 s[12:13], vcc
	s_cbranch_execz .LBB0_611
	s_bcnt1_i32_b64 s10, s[10:11]

; __device__ __forceinline__ unsigned cvt_pk_bf16(float lo, float hi) { unsigned r; asm volatile("v_cvt_pk_bf16_f32 %0, %1, %2" : "=v"(r) : "v"(lo), "v"(hi)); return r; }
; __device__ __forceinline__ float bf_lo(unsigned w) { return __uint_as_float(w << 16); }
; __device__ __forceinline__ float bf_hi(unsigned w) { return __uint_as_float(w & 0xffff0000u); }
; __global__ void __launch_bounds__(NTHR, 2) hybrid_block_fwd(Args a) {
;     ...
;         for (int i = 0; i < CH_L; ++i) {
;             const u32x2 q = pab[(size_t)i * (LW / 2)]; const f32x2 av = (f32x2){__builtin_amdgcn_exp2f(bf_lo(q.x)), __builtin_amdgcn_exp2f(bf_lo(q.y))}, bv = (f32x2){bf_hi(q.x), bf_hi(q.y)}; const unsigned gq = pg[(size_t)i * (LW / 2)];
;             H = av * H + bv;
;             po[(size_t)i * (KC / 2)] = cvt_pk_bf16(H.x * bf_lo(gq), H.y * bf_hi(gq));
;         }
.Lp2d_steady:
	s_waitcnt vmcnt(45)
	v_lshlrev_b32_e32 v8, 16, v32
	v_lshlrev_b32_e32 v9, 16, v33
	v_exp_f32_e32 v8, v8
	v_exp_f32_e32 v9, v9
	v_and_b32_e32 v10, 0xffff0000, v32
	v_and_b32_e32 v11, 0xffff0000, v33
	v_lshlrev_b32_e32 v12, 16, v64
	v_and_b32_e32 v13, 0xffff0000, v64
	v_pk_fma_f32 v[4:5], v[4:5], v[8:9], v[10:11]
	v_mul_f32_e32 v12, v4, v12
	v_mul_f32_e32 v13, v5, v13
	v_cvt_pk_bf16_f32 v12, v12, v13
	global_store_dword v3, v12, s[18:19]
	s_add_u32 s18, s18, 0x1800
	s_addc_u32 s19, s19, 0
	global_load_dwordx2 v[32:33], v2, s[12:13] nt
	global_load_dword v64, v3, s[14:15] nt
	s_add_u32 s12, s12, 0x2000
	s_addc_u32 s13, s13, 0
	s_add_u32 s14, s14, 0x1000
	s_addc_u32 s15, s15, 0
	s_waitcnt vmcnt(45)
	v_lshlrev_b32_e32 v16, 16, v34
	v_lshlrev_b32_e32 v17, 16, v35
	v_exp_f32_e32 v16, v16
	v_exp_f32_e32 v17, v17
	v_and_b32_e32 v18, 0xffff0000, v34
	v_and_b32_e32 v19, 0xffff0000, v35
	v_lshlrev_b32_e32 v20, 16, v65
	v_and_b32_e32 v21, 0xffff0000, v65
	v_pk_fma_f32 v[4:5], v[4:5], v[16:17], v[18:19]
	v_mul_f32_e32 v20, v4, v20
	v_mul_f32_e32 v21, v5, v21
	v_cvt_pk_bf16_f32 v20, v20, v21
	global_store_dword v3, v20, s[18:19]
	s_add_u32 s18, s18, 0x1800
	s_addc_u32 s19, s19, 0
	global_load_dwordx2 v[34:35], v2, s[12:13] nt
	global_load_dword v65, v3, s[14:15] nt
	s_add_u32 s12, s12, 0x2000
	s_addc_u32 s13, s13, 0
	s_add_u32 s14, s14, 0x1000
	s_addc_u32 s15, s15, 0
	s_waitcnt vmcnt(45)
	v_lshlrev_b32_e32 v8, 16, v36
	v_lshlrev_b32_e32 v9, 16, v37
	v_exp_f32_e32 v8, v8
	v_exp_f32_e32 v9, v9
	v_and_b32_e32 v10, 0xffff0000, v36
	v_and_b32_e32 v11, 0xffff0000, v37
	v_lshlrev_b32_e32 v12, 16, v66
	v_and_b32_e32 v13, 0xffff0000, v66
	v_pk_fma_f32 v[4:5], v[4:5], v[8:9], v[10:11]
	v_mul_f32_e32 v12, v4, v12
	v_mul_f32_e32 v13, v5, v13
	v_cvt_pk_bf16_f32 v12, v12, v13
	global_store_dword v3, v12, s[18:19]
	s_add_u32 s18, s18, 0x1800
	s_addc_u32 s19, s19, 0
	global_load_dwordx2 v[36:37], v2, s[12:13] nt
	global_load_dword v66, v3, s[14:15] nt
	s_add_u32 s12, s12, 0x2000
	s_addc_u32 s13, s13, 0
	s_add_u32 s14, s14, 0x1000
	s_addc_u32 s15, s15, 0
	s_waitcnt vmcnt(45)
	v_lshlrev_b32_e32 v16, 16, v38
	v_lshlrev_b32_e32 v17, 16, v39
	v_exp_f32_e32 v16, v16
	v_exp_f32_e32 v17, v17
	v_and_b32_e32 v18, 0xffff0000, v38
	v_and_b32_e32 v19, 0xffff0000, v39
	v_lshlrev_b32_e32 v20, 16, v67
	v_and_b32_e32 v21, 0xffff0000, v67
	v_pk_fma_f32 v[4:5], v[4:5], v[16:17], v[18:19]
	v_mul_f32_e32 v20, v4, v20
	v_mul_f32_e32 v21, v5, v21
	v_cvt_pk_bf16_f32 v20, v20, v21
	global_store_dword v3, v20, s[18:19]
	s_add_u32 s18, s18, 0x1800
	s_addc_u32 s19, s19, 0
	global_load_dwordx2 v[38:39], v2, s[12:13] nt
	global_load_dword v67, v3, s[14:15] nt
	s_add_u32 s12, s12, 0x2000
	s_addc_u32 s13, s13, 0
	s_add_u32 s14, s14, 0x1000
	s_addc_u32 s15, s15, 0
	s_waitcnt vmcnt(45)
	v_lshlrev_b32_e32 v8, 16, v40
	v_lshlrev_b32_e32 v9, 16, v41
	v_exp_f32_e32 v8, v8
	v_exp_f32_e32 v9, v9
	v_and_b32_e32 v10, 0xffff0000, v40
	v_and_b32_e32 v11, 0xffff0000, v41
	v_lshlrev_b32_e32 v12, 16, v68
	v_and_b32_e32 v13, 0xffff0000, v68
	v_pk_fma_f32 v[4:5], v[4:5], v[8:9], v[10:11]
	v_mul_f32_e32 v12, v4, v12
	v_mul_f32_e32 v13, v5, v13
	v_cvt_pk_bf16_f32 v12, v12, v13
	global_store_dword v3, v12, s[18:19]
	s_add_u32 s18, s18, 0x1800
	s_addc_u32 s19, s19, 0
	global_load_dwordx2 v[40:41], v2, s[12:13] nt
	global_load_dword v68, v3, s[14:15] nt
	s_add_u32 s12, s12, 0x2000
	s_addc_u32 s13, s13, 0
	s_add_u32 s14, s14, 0x1000
	s_addc_u32 s15, s15, 0
	s_waitcnt vmcnt(45)
	v_lshlrev_b32_e32 v16, 16, v42
	v_lshlrev_b32_e32 v17, 16, v43
	v_exp_f32_e32 v16, v16
	v_exp_f32_e32 v17, v17
	v_and_b32_e32 v18, 0xffff0000, v42
	v_and_b32_e32 v19, 0xffff0000, v43
	v_lshlrev_b32_e32 v20, 16, v69
	v_and_b32_e32 v21, 0xffff0000, v69
	v_pk_fma_f32 v[4:5], v[4:5], v[16:17], v[18:19]
	v_mul_f32_e32 v20, v4, v20
	v_mul_f32_e32 v21, v5, v21
	v_cvt_pk_bf16_f32 v20, v20, v21
	global_store_dword v3, v20, s[18:19]
	s_add_u32 s18, s18, 0x1800
	s_addc_u32 s19, s19, 0
	global_load_dwordx2 v[42:43], v2, s[12:13] nt
	global_load_dword v69, v3, s[14:15] nt
	s_add_u32 s12, s12, 0x2000
	s_addc_u32 s13, s13, 0
	s_add_u32 s14, s14, 0x1000
	s_addc_u32 s15, s15, 0
	s_waitcnt vmcnt(45)
	v_lshlrev_b32_e32 v8, 16, v44
	v_lshlrev_b32_e32 v9, 16, v45
	v_exp_f32_e32 v8, v8
	v_exp_f32_e32 v9, v9
	v_and_b32_e32 v10, 0xffff0000, v44
	v_and_b32_e32 v11, 0xffff0000, v45
	v_lshlrev_b32_e32 v12, 16, v70
	v_and_b32_e32 v13, 0xffff0000, v70
	v_pk_fma_f32 v[4:5], v[4:5], v[8:9], v[10:11]
	v_mul_f32_e32 v12, v4, v12
	v_mul_f32_e32 v13, v5, v13
	v_cvt_pk_bf16_f32 v12, v12, v13
	global_store_dword v3, v12, s[18:19]
	s_add_u32 s18, s18, 0x1800
	s_addc_u32 s19, s19, 0
	global_load_dwordx2 v[44:45], v2, s[12:13] nt
	global_load_dword v70, v3, s[14:15] nt
	s_add_u32 s12, s12, 0x2000
	s_addc_u32 s13, s13, 0
	s_add_u32 s14, s14, 0x1000
	s_addc_u32 s15, s15, 0
	s_waitcnt vmcnt(45)
	v_lshlrev_b32_e32 v16, 16, v46
	v_lshlrev_b32_e32 v17, 16, v47
	v_exp_f32_e32 v16, v16
	v_exp_f32_e32 v17, v17
	v_and_b32_e32 v18, 0xffff0000, v46
	v_and_b32_e32 v19, 0xffff0000, v47
	v_lshlrev_b32_e32 v20, 16, v71
	v_and_b32_e32 v21, 0xffff0000, v71
	v_pk_fma_f32 v[4:5], v[4:5], v[16:17], v[18:19]
	v_mul_f32_e32 v20, v4, v20
	v_mul_f32_e32 v21, v5, v21
	v_cvt_pk_bf16_f32 v20, v20, v21
	global_store_dword v3, v20, s[18:19]
	s_add_u32 s18, s18, 0x1800
	s_addc_u32 s19, s19, 0
	global_load_dwordx2 v[46:47], v2, s[12:13] nt
	global_load_dword v71, v3, s[14:15] nt
	s_add_u32 s12, s12, 0x2000
	s_addc_u32 s13, s13, 0
	s_add_u32 s14, s14, 0x1000
	s_addc_u32 s15, s15, 0
	s_waitcnt vmcnt(45)
; __device__ __forceinline__ unsigned cvt_pk_bf16(float lo, float hi) { unsigned r; asm volatile("v_cvt_pk_bf16_f32 %0, %1, %2" : "=v"(r) : "v"(lo), "v"(hi)); return r; }
; __device__ __forceinline__ float bf_lo(unsigned w) { return __uint_as_float(w << 16); }
; __device__ __forceinline__ float bf_hi(unsigned w) { return __uint_as_float(w & 0xffff0000u); }
; __global__ void __launch_bounds__(NTHR, 2) hybrid_block_fwd(Args a) {
;     ...
;         for (int i = 0; i < CH_L; ++i) {
;             const u32x2 q = pab[(size_t)i * (LW / 2)]; const f32x2 av = (f32x2){__builtin_amdgcn_exp2f(bf_lo(q.x)), __builtin_amdgcn_exp2f(bf_lo(q.y))}, bv = (f32x2){bf_hi(q.x), bf_hi(q.y)}; const unsigned gq = pg[(size_t)i * (LW / 2)];
;             H = av * H + bv;
;             po[(size_t)i * (KC / 2)] = cvt_pk_bf16(H.x * bf_lo(gq), H.y * bf_hi(gq));
;         }
	v_lshlrev_b32_e32 v8, 16, v48
	v_lshlrev_b32_e32 v9, 16, v49
	v_exp_f32_e32 v8, v8
	v_exp_f32_e32 v9, v9
	v_and_b32_e32 v10, 0xffff0000, v48
	v_and_b32_e32 v11, 0xffff0000, v49
	v_lshlrev_b32_e32 v12, 16, v72
	v_and_b32_e32 v13, 0xffff0000, v72
	v_pk_fma_f32 v[4:5], v[4:5], v[8:9], v[10:11]
	v_mul_f32_e32 v12, v4, v12
	v_mul_f32_e32 v13, v5, v13
	v_cvt_pk_bf16_f32 v12, v12, v13
	global_store_dword v3, v12, s[18:19]
	s_add_u32 s18, s18, 0x1800
	s_addc_u32 s19, s19, 0
	global_load_dwordx2 v[48:49], v2, s[12:13] nt
	global_load_dword v72, v3, s[14:15] nt
	s_add_u32 s12, s12, 0x2000
	s_addc_u32 s13, s13, 0
	s_add_u32 s14, s14, 0x1000
	s_addc_u32 s15, s15, 0
	s_waitcnt vmcnt(45)
	v_lshlrev_b32_e32 v16, 16, v50
	v_lshlrev_b32_e32 v17, 16, v51
	v_exp_f32_e32 v16, v16
	v_exp_f32_e32 v17, v17
	v_and_b32_e32 v18, 0xffff0000, v50
	v_and_b32_e32 v19, 0xffff0000, v51
	v_lshlrev_b32_e32 v20, 16, v73
	v_and_b32_e32 v21, 0xffff0000, v73
	v_pk_fma_f32 v[4:5], v[4:5], v[16:17], v[18:19]
	v_mul_f32_e32 v20, v4, v20
	v_mul_f32_e32 v21, v5, v21
	v_cvt_pk_bf16_f32 v20, v20, v21
	global_store_dword v3, v20, s[18:19]
	s_add_u32 s18, s18, 0x1800
	s_addc_u32 s19, s19, 0
	global_load_dwordx2 v[50:51], v2, s[12:13] nt
	global_load_dword v73, v3, s[14:15] nt
	s_add_u32 s12, s12, 0x2000
	s_addc_u32 s13, s13, 0
	s_add_u32 s14, s14, 0x1000
	s_addc_u32 s15, s15, 0
	s_waitcnt vmcnt(45)
	v_lshlrev_b32_e32 v8, 16, v52
	v_lshlrev_b32_e32 v9, 16, v53
	v_exp_f32_e32 v8, v8
	v_exp_f32_e32 v9, v9
	v_and_b32_e32 v10, 0xffff0000, v52
	v_and_b32_e32 v11, 0xffff0000, v53
	v_lshlrev_b32_e32 v12, 16, v74
	v_and_b32_e32 v13, 0xffff0000, v74
	v_pk_fma_f32 v[4:5], v[4:5], v[8:9], v[10:11]
	v_mul_f32_e32 v12, v4, v12
	v_mul_f32_e32 v13, v5, v13
	v_cvt_pk_bf16_f32 v12, v12, v13
	global_store_dword v3, v12, s[18:19]
	s_add_u32 s18, s18, 0x1800
	s_addc_u32 s19, s19, 0
	global_load_dwordx2 v[52:53], v2, s[12:13] nt
	global_load_dword v74, v3, s[14:15] nt
	s_add_u32 s12, s12, 0x2000
	s_addc_u32 s13, s13, 0
	s_add_u32 s14, s14, 0x1000
	s_addc_u32 s15, s15, 0
	s_waitcnt vmcnt(45)
	v_lshlrev_b32_e32 v16, 16, v54
	v_lshlrev_b32_e32 v17, 16, v55
	v_exp_f32_e32 v16, v16
	v_exp_f32_e32 v17, v17
	v_and_b32_e32 v18, 0xffff0000, v54
	v_and_b32_e32 v19, 0xffff0000, v55
	v_lshlrev_b32_e32 v20, 16, v75
	v_and_b32_e32 v21, 0xffff0000, v75
	v_pk_fma_f32 v[4:5], v[4:5], v[16:17], v[18:19]
	v_mul_f32_e32 v20, v4, v20
	v_mul_f32_e32 v21, v5, v21
	v_cvt_pk_bf16_f32 v20, v20, v21
	global_store_dword v3, v20, s[18:19]
	s_add_u32 s18, s18, 0x1800
	s_addc_u32 s19, s19, 0
	global_load_dwordx2 v[54:55], v2, s[12:13] nt
	global_load_dword v75, v3, s[14:15] nt
	s_add_u32 s12, s12, 0x2000
	s_addc_u32 s13, s13, 0
	s_add_u32 s14, s14, 0x1000
	s_addc_u32 s15, s15, 0
	s_waitcnt vmcnt(45)
	v_lshlrev_b32_e32 v8, 16, v56
	v_lshlrev_b32_e32 v9, 16, v57
	v_exp_f32_e32 v8, v8
	v_exp_f32_e32 v9, v9
	v_and_b32_e32 v10, 0xffff0000, v56
	v_and_b32_e32 v11, 0xffff0000, v57
	v_lshlrev_b32_e32 v12, 16, v76
	v_and_b32_e32 v13, 0xffff0000, v76
	v_pk_fma_f32 v[4:5], v[4:5], v[8:9], v[10:11]
	v_mul_f32_e32 v12, v4, v12
	v_mul_f32_e32 v13, v5, v13
	v_cvt_pk_bf16_f32 v12, v12, v13
	global_store_dword v3, v12, s[18:19]
	s_add_u32 s18, s18, 0x1800
	s_addc_u32 s19, s19, 0
	global_load_dwordx2 v[56:57], v2, s[12:13] nt
	global_load_dword v76, v3, s[14:15] nt
	s_add_u32 s12, s12, 0x2000
	s_addc_u32 s13, s13, 0
	s_add_u32 s14, s14, 0x1000
	s_addc_u32 s15, s15, 0
	s_waitcnt vmcnt(45)
	v_lshlrev_b32_e32 v16, 16, v58
	v_lshlrev_b32_e32 v17, 16, v59
	v_exp_f32_e32 v16, v16
	v_exp_f32_e32 v17, v17
	v_and_b32_e32 v18, 0xffff0000, v58
	v_and_b32_e32 v19, 0xffff0000, v59
	v_lshlrev_b32_e32 v20, 16, v77
	v_and_b32_e32 v21, 0xffff0000, v77
	v_pk_fma_f32 v[4:5], v[4:5], v[16:17], v[18:19]
	v_mul_f32_e32 v20, v4, v20
	v_mul_f32_e32 v21, v5, v21
	v_cvt_pk_bf16_f32 v20, v20, v21
	global_store_dword v3, v20, s[18:19]
	s_add_u32 s18, s18, 0x1800
	s_addc_u32 s19, s19, 0
	global_load_dwordx2 v[58:59], v2, s[12:13] nt
	global_load_dword v77, v3, s[14:15] nt
	s_add_u32 s12, s12, 0x2000
	s_addc_u32 s13, s13, 0
	s_add_u32 s14, s14, 0x1000
	s_addc_u32 s15, s15, 0
	s_waitcnt vmcnt(45)
	v_lshlrev_b32_e32 v8, 16, v60
	v_lshlrev_b32_e32 v9, 16, v61
	v_exp_f32_e32 v8, v8
	v_exp_f32_e32 v9, v9
	v_and_b32_e32 v10, 0xffff0000, v60
	v_and_b32_e32 v11, 0xffff0000, v61
	v_lshlrev_b32_e32 v12, 16, v78
	v_and_b32_e32 v13, 0xffff0000, v78
	v_pk_fma_f32 v[4:5], v[4:5], v[8:9], v[10:11]
	v_mul_f32_e32 v12, v4, v12
	v_mul_f32_e32 v13, v5, v13
	v_cvt_pk_bf16_f32 v12, v12, v13
	global_store_dword v3, v12, s[18:19]
	s_add_u32 s18, s18, 0x1800
	s_addc_u32 s19, s19, 0
	global_load_dwordx2 v[60:61], v2, s[12:13] nt
	global_load_dword v78, v3, s[14:15] nt
	s_add_u32 s12, s12, 0x2000
	s_addc_u32 s13, s13, 0
	s_add_u32 s14, s14, 0x1000
	s_addc_u32 s15, s15, 0
	s_waitcnt vmcnt(45)
	v_lshlrev_b32_e32 v16, 16, v62
	v_lshlrev_b32_e32 v17, 16, v63
	v_exp_f32_e32 v16, v16
	v_exp_f32_e32 v17, v17
	v_and_b32_e32 v18, 0xffff0000, v62
	v_and_b32_e32 v19, 0xffff0000, v63
	v_lshlrev_b32_e32 v20, 16, v79
	v_and_b32_e32 v21, 0xffff0000, v79
	v_pk_fma_f32 v[4:5], v[4:5], v[16:17], v[18:19]
	v_mul_f32_e32 v20, v4, v20
	v_mul_f32_e32 v21, v5, v21
	v_cvt_pk_bf16_f32 v20, v20, v21
	global_store_dword v3, v20, s[18:19]
	s_add_u32 s18, s18, 0x1800
	s_addc_u32 s19, s19, 0
	global_load_dwordx2 v[62:63], v2, s[12:13] nt
	global_load_dword v79, v3, s[14:15] nt
	s_add_u32 s12, s12, 0x2000
	s_addc_u32 s13, s13, 0
	s_add_u32 s14, s14, 0x1000
	s_addc_u32 s15, s15, 0
	s_sub_u32 s22, s22, 1
	s_cmp_lg_u32 s22, 0
	s_cbranch_scc1 .Lp2d_steady
; __device__ __forceinline__ unsigned cvt_pk_bf16(float lo, float hi) { unsigned r; asm volatile("v_cvt_pk_bf16_f32 %0, %1, %2" : "=v"(r) : "v"(lo), "v"(hi)); return r; }
; __device__ __forceinline__ float bf_lo(unsigned w) { return __uint_as_float(w << 16); }
; __device__ __forceinline__ float bf_hi(unsigned w) { return __uint_as_float(w & 0xffff0000u); }
; __global__ void __launch_bounds__(NTHR, 2) hybrid_block_fwd(Args a) {
;     ...
;         for (int i = 0; i < CH_L; ++i) {
;             const u32x2 q = pab[(size_t)i * (LW / 2)]; const f32x2 av = (f32x2){__builtin_amdgcn_exp2f(bf_lo(q.x)), __builtin_amdgcn_exp2f(bf_lo(q.y))}, bv = (f32x2){bf_hi(q.x), bf_hi(q.y)}; const unsigned gq = pg[(size_t)i * (LW / 2)];
;             H = av * H + bv;
;             po[(size_t)i * (KC / 2)] = cvt_pk_bf16(H.x * bf_lo(gq), H.y * bf_hi(gq));
;         }
	s_waitcnt vmcnt(45)
	v_lshlrev_b32_e32 v8, 16, v32
	v_lshlrev_b32_e32 v9, 16, v33
	v_exp_f32_e32 v8, v8
	v_exp_f32_e32 v9, v9
	v_and_b32_e32 v10, 0xffff0000, v32
	v_and_b32_e32 v11, 0xffff0000, v33
	v_lshlrev_b32_e32 v12, 16, v64
	v_and_b32_e32 v13, 0xffff0000, v64
	v_pk_fma_f32 v[4:5], v[4:5], v[8:9], v[10:11]
	v_mul_f32_e32 v12, v4, v12
	v_mul_f32_e32 v13, v5, v13
	v_cvt_pk_bf16_f32 v12, v12, v13
	global_store_dword v3, v12, s[18:19]
	s_add_u32 s18, s18, 0x1800
	s_addc_u32 s19, s19, 0
	s_waitcnt vmcnt(43)
	v_lshlrev_b32_e32 v16, 16, v34
	v_lshlrev_b32_e32 v17, 16, v35
	v_exp_f32_e32 v16, v16
	v_exp_f32_e32 v17, v17
	v_and_b32_e32 v18, 0xffff0000, v34
	v_and_b32_e32 v19, 0xffff0000, v35
	v_lshlrev_b32_e32 v20, 16, v65
	v_and_b32_e32 v21, 0xffff0000, v65
	v_pk_fma_f32 v[4:5], v[4:5], v[16:17], v[18:19]
	v_mul_f32_e32 v20, v4, v20
	v_mul_f32_e32 v21, v5, v21
	v_cvt_pk_bf16_f32 v20, v20, v21
	global_store_dword v3, v20, s[18:19]
	s_add_u32 s18, s18, 0x1800
	s_addc_u32 s19, s19, 0
	s_waitcnt vmcnt(41)
	v_lshlrev_b32_e32 v8, 16, v36
	v_lshlrev_b32_e32 v9, 16, v37
	v_exp_f32_e32 v8, v8
	v_exp_f32_e32 v9, v9
	v_and_b32_e32 v10, 0xffff0000, v36
	v_and_b32_e32 v11, 0xffff0000, v37
	v_lshlrev_b32_e32 v12, 16, v66
	v_and_b32_e32 v13, 0xffff0000, v66
	v_pk_fma_f32 v[4:5], v[4:5], v[8:9], v[10:11]
	v_mul_f32_e32 v12, v4, v12
	v_mul_f32_e32 v13, v5, v13
	v_cvt_pk_bf16_f32 v12, v12, v13
	global_store_dword v3, v12, s[18:19]
	s_add_u32 s18, s18, 0x1800
	s_addc_u32 s19, s19, 0
	s_waitcnt vmcnt(39)
	v_lshlrev_b32_e32 v16, 16, v38
	v_lshlrev_b32_e32 v17, 16, v39
	v_exp_f32_e32 v16, v16
	v_exp_f32_e32 v17, v17
	v_and_b32_e32 v18, 0xffff0000, v38
	v_and_b32_e32 v19, 0xffff0000, v39
	v_lshlrev_b32_e32 v20, 16, v67
	v_and_b32_e32 v21, 0xffff0000, v67
	v_pk_fma_f32 v[4:5], v[4:5], v[16:17], v[18:19]
	v_mul_f32_e32 v20, v4, v20
	v_mul_f32_e32 v21, v5, v21
	v_cvt_pk_bf16_f32 v20, v20, v21
	global_store_dword v3, v20, s[18:19]
	s_add_u32 s18, s18, 0x1800
	s_addc_u32 s19, s19, 0
	s_waitcnt vmcnt(37)
	v_lshlrev_b32_e32 v8, 16, v40
	v_lshlrev_b32_e32 v9, 16, v41
	v_exp_f32_e32 v8, v8
	v_exp_f32_e32 v9, v9
	v_and_b32_e32 v10, 0xffff0000, v40
	v_and_b32_e32 v11, 0xffff0000, v41
	v_lshlrev_b32_e32 v12, 16, v68
	v_and_b32_e32 v13, 0xffff0000, v68
	v_pk_fma_f32 v[4:5], v[4:5], v[8:9], v[10:11]
	v_mul_f32_e32 v12, v4, v12
	v_mul_f32_e32 v13, v5, v13
	v_cvt_pk_bf16_f32 v12, v12, v13
	global_store_dword v3, v12, s[18:19]
	s_add_u32 s18, s18, 0x1800
	s_addc_u32 s19, s19, 0
	s_waitcnt vmcnt(35)
	v_lshlrev_b32_e32 v16, 16, v42
	v_lshlrev_b32_e32 v17, 16, v43
	v_exp_f32_e32 v16, v16
	v_exp_f32_e32 v17, v17
	v_and_b32_e32 v18, 0xffff0000, v42
	v_and_b32_e32 v19, 0xffff0000, v43
	v_lshlrev_b32_e32 v20, 16, v69
	v_and_b32_e32 v21, 0xffff0000, v69
	v_pk_fma_f32 v[4:5], v[4:5], v[16:17], v[18:19]
	v_mul_f32_e32 v20, v4, v20
	v_mul_f32_e32 v21, v5, v21
	v_cvt_pk_bf16_f32 v20, v20, v21
	global_store_dword v3, v20, s[18:19]
	s_add_u32 s18, s18, 0x1800
	s_addc_u32 s19, s19, 0
	s_waitcnt vmcnt(33)
	v_lshlrev_b32_e32 v8, 16, v44
	v_lshlrev_b32_e32 v9, 16, v45
	v_exp_f32_e32 v8, v8
	v_exp_f32_e32 v9, v9
	v_and_b32_e32 v10, 0xffff0000, v44
	v_and_b32_e32 v11, 0xffff0000, v45
	v_lshlrev_b32_e32 v12, 16, v70
	v_and_b32_e32 v13, 0xffff0000, v70
	v_pk_fma_f32 v[4:5], v[4:5], v[8:9], v[10:11]
	v_mul_f32_e32 v12, v4, v12
	v_mul_f32_e32 v13, v5, v13
	v_cvt_pk_bf16_f32 v12, v12, v13
	global_store_dword v3, v12, s[18:19]
	s_add_u32 s18, s18, 0x1800
	s_addc_u32 s19, s19, 0
	s_waitcnt vmcnt(31)
	v_lshlrev_b32_e32 v16, 16, v46
	v_lshlrev_b32_e32 v17, 16, v47
	v_exp_f32_e32 v16, v16
	v_exp_f32_e32 v17, v17
	v_and_b32_e32 v18, 0xffff0000, v46
	v_and_b32_e32 v19, 0xffff0000, v47
	v_lshlrev_b32_e32 v20, 16, v71
	v_and_b32_e32 v21, 0xffff0000, v71
	v_pk_fma_f32 v[4:5], v[4:5], v[16:17], v[18:19]
	v_mul_f32_e32 v20, v4, v20
	v_mul_f32_e32 v21, v5, v21
	v_cvt_pk_bf16_f32 v20, v20, v21
	global_store_dword v3, v20, s[18:19]
	s_add_u32 s18, s18, 0x1800
	s_addc_u32 s19, s19, 0
	s_waitcnt vmcnt(29)
	v_lshlrev_b32_e32 v8, 16, v48
	v_lshlrev_b32_e32 v9, 16, v49
	v_exp_f32_e32 v8, v8
	v_exp_f32_e32 v9, v9
	v_and_b32_e32 v10, 0xffff0000, v48
	v_and_b32_e32 v11, 0xffff0000, v49
	v_lshlrev_b32_e32 v12, 16, v72
	v_and_b32_e32 v13, 0xffff0000, v72
	v_pk_fma_f32 v[4:5], v[4:5], v[8:9], v[10:11]
	v_mul_f32_e32 v12, v4, v12
	v_mul_f32_e32 v13, v5, v13
	v_cvt_pk_bf16_f32 v12, v12, v13
	global_store_dword v3, v12, s[18:19]
	s_add_u32 s18, s18, 0x1800
	s_addc_u32 s19, s19, 0
	s_waitcnt vmcnt(27)
	v_lshlrev_b32_e32 v16, 16, v50
	v_lshlrev_b32_e32 v17, 16, v51
	v_exp_f32_e32 v16, v16
	v_exp_f32_e32 v17, v17
	v_and_b32_e32 v18, 0xffff0000, v50
	v_and_b32_e32 v19, 0xffff0000, v51
	v_lshlrev_b32_e32 v20, 16, v73
	v_and_b32_e32 v21, 0xffff0000, v73
	v_pk_fma_f32 v[4:5], v[4:5], v[16:17], v[18:19]
	v_mul_f32_e32 v20, v4, v20
	v_mul_f32_e32 v21, v5, v21
	v_cvt_pk_bf16_f32 v20, v20, v21
	global_store_dword v3, v20, s[18:19]
	s_add_u32 s18, s18, 0x1800
	s_addc_u32 s19, s19, 0
	s_waitcnt vmcnt(25)
; __device__ __forceinline__ unsigned cvt_pk_bf16(float lo, float hi) { unsigned r; asm volatile("v_cvt_pk_bf16_f32 %0, %1, %2" : "=v"(r) : "v"(lo), "v"(hi)); return r; }
; __device__ __forceinline__ float bf_lo(unsigned w) { return __uint_as_float(w << 16); }
; __device__ __forceinline__ float bf_hi(unsigned w) { return __uint_as_float(w & 0xffff0000u); }
; __device__ __forceinline__ unsigned xb_add(unsigned* p, unsigned v) { return __hip_atomic_fetch_add(p, v, __ATOMIC_RELAXED, __HIP_MEMORY_SCOPE_AGENT); }
; __device__ __forceinline__ void xcd_barrier(const XcdBarrier& b) {
;     asm volatile("s_waitcnt vmcnt(0)" ::: "memory");
;     __syncthreads();
;     if (threadIdx.x == 0) {
;         unsigned* bar = b.bar;
;         __builtin_amdgcn_s_waitcnt(0);
;         unsigned nloc = b.st[0], nx = b.st[1];
;         if (nloc == 0u) { xcd_barrier_complete(bar, b.x, nloc, nx); b.st[0] = nloc; b.st[1] = nx; }
;         const unsigned old = xb_add(&bar[XB_XSUB(b.x)], 1u);
;         const unsigned gen = old / nloc;
;         if (old + 1u == (gen + 1u) * nloc) {
; __global__ void __launch_bounds__(NTHR, 2) hybrid_block_fwd(Args a) {
;     ...
;         for (int i = 0; i < CH_L; ++i) {
;             const u32x2 q = pab[(size_t)i * (LW / 2)]; const f32x2 av = (f32x2){__builtin_amdgcn_exp2f(bf_lo(q.x)), __builtin_amdgcn_exp2f(bf_lo(q.y))}, bv = (f32x2){bf_hi(q.x), bf_hi(q.y)}; const unsigned gq = pg[(size_t)i * (LW / 2)];
;             H = av * H + bv;
;             po[(size_t)i * (KC / 2)] = cvt_pk_bf16(H.x * bf_lo(gq), H.y * bf_hi(gq));
;         }
	v_lshlrev_b32_e32 v8, 16, v52
	v_lshlrev_b32_e32 v9, 16, v53
	v_exp_f32_e32 v8, v8
	v_exp_f32_e32 v9, v9
	v_and_b32_e32 v10, 0xffff0000, v52
	v_and_b32_e32 v11, 0xffff0000, v53
	v_lshlrev_b32_e32 v12, 16, v74
	v_and_b32_e32 v13, 0xffff0000, v74
	v_pk_fma_f32 v[4:5], v[4:5], v[8:9], v[10:11]
	v_mul_f32_e32 v12, v4, v12
	v_mul_f32_e32 v13, v5, v13
	v_cvt_pk_bf16_f32 v12, v12, v13
	global_store_dword v3, v12, s[18:19]
	s_add_u32 s18, s18, 0x1800
	s_addc_u32 s19, s19, 0
	s_waitcnt vmcnt(23)
	v_lshlrev_b32_e32 v16, 16, v54
	v_lshlrev_b32_e32 v17, 16, v55
	v_exp_f32_e32 v16, v16
	v_exp_f32_e32 v17, v17
	v_and_b32_e32 v18, 0xffff0000, v54
	v_and_b32_e32 v19, 0xffff0000, v55
	v_lshlrev_b32_e32 v20, 16, v75
	v_and_b32_e32 v21, 0xffff0000, v75
	v_pk_fma_f32 v[4:5], v[4:5], v[16:17], v[18:19]
	v_mul_f32_e32 v20, v4, v20
	v_mul_f32_e32 v21, v5, v21
	v_cvt_pk_bf16_f32 v20, v20, v21
	global_store_dword v3, v20, s[18:19]
	s_add_u32 s18, s18, 0x1800
	s_addc_u32 s19, s19, 0
	s_waitcnt vmcnt(21)
	v_lshlrev_b32_e32 v8, 16, v56
	v_lshlrev_b32_e32 v9, 16, v57
	v_exp_f32_e32 v8, v8
	v_exp_f32_e32 v9, v9
	v_and_b32_e32 v10, 0xffff0000, v56
	v_and_b32_e32 v11, 0xffff0000, v57
	v_lshlrev_b32_e32 v12, 16, v76
	v_and_b32_e32 v13, 0xffff0000, v76
	v_pk_fma_f32 v[4:5], v[4:5], v[8:9], v[10:11]
	v_mul_f32_e32 v12, v4, v12
	v_mul_f32_e32 v13, v5, v13
	v_cvt_pk_bf16_f32 v12, v12, v13
	global_store_dword v3, v12, s[18:19]
	s_add_u32 s18, s18, 0x1800
	s_addc_u32 s19, s19, 0
	s_waitcnt vmcnt(19)
	v_lshlrev_b32_e32 v16, 16, v58
	v_lshlrev_b32_e32 v17, 16, v59
	v_exp_f32_e32 v16, v16
	v_exp_f32_e32 v17, v17
	v_and_b32_e32 v18, 0xffff0000, v58
	v_and_b32_e32 v19, 0xffff0000, v59
	v_lshlrev_b32_e32 v20, 16, v77
	v_and_b32_e32 v21, 0xffff0000, v77
	v_pk_fma_f32 v[4:5], v[4:5], v[16:17], v[18:19]
	v_mul_f32_e32 v20, v4, v20
	v_mul_f32_e32 v21, v5, v21
	v_cvt_pk_bf16_f32 v20, v20, v21
	global_store_dword v3, v20, s[18:19]
	s_add_u32 s18, s18, 0x1800
	s_addc_u32 s19, s19, 0
	s_waitcnt vmcnt(17)
	v_lshlrev_b32_e32 v8, 16, v60
	v_lshlrev_b32_e32 v9, 16, v61
	v_exp_f32_e32 v8, v8
	v_exp_f32_e32 v9, v9
	v_and_b32_e32 v10, 0xffff0000, v60
	v_and_b32_e32 v11, 0xffff0000, v61
	v_lshlrev_b32_e32 v12, 16, v78
	v_and_b32_e32 v13, 0xffff0000, v78
	v_pk_fma_f32 v[4:5], v[4:5], v[8:9], v[10:11]
	v_mul_f32_e32 v12, v4, v12
	v_mul_f32_e32 v13, v5, v13
	v_cvt_pk_bf16_f32 v12, v12, v13
	global_store_dword v3, v12, s[18:19]
	s_add_u32 s18, s18, 0x1800
	s_addc_u32 s19, s19, 0
	s_waitcnt vmcnt(15)
	v_lshlrev_b32_e32 v16, 16, v62
	v_lshlrev_b32_e32 v17, 16, v63
	v_exp_f32_e32 v16, v16
	v_exp_f32_e32 v17, v17
	v_and_b32_e32 v18, 0xffff0000, v62
	v_and_b32_e32 v19, 0xffff0000, v63
	v_lshlrev_b32_e32 v20, 16, v79
	v_and_b32_e32 v21, 0xffff0000, v79
	v_pk_fma_f32 v[4:5], v[4:5], v[16:17], v[18:19]
	v_mul_f32_e32 v20, v4, v20
	v_mul_f32_e32 v21, v5, v21
	v_cvt_pk_bf16_f32 v20, v20, v21
	global_store_dword v3, v20, s[18:19]
	s_add_u32 s18, s18, 0x1800
	s_addc_u32 s19, s19, 0
	s_waitcnt vmcnt(0)
	s_barrier
	v_readfirstlane_b32 s0, v212
	s_cmp_lg_u32 s0, 64
	s_cbranch_scc1 .Linv_4
	buffer_inv sc1
	s_waitcnt vmcnt(0)
.Linv_4:
	s_mov_b64 s[0:1], exec
	v_readlane_b32 s4, v248, 6
	v_readlane_b32 s5, v248, 7
	s_and_b64 s[4:5], s[0:1], s[4:5]
	s_mov_b64 exec, s[4:5]
	s_cbranch_execz .LBB0_735
	s_add_i32 s4, 0, 0x20020
	v_mov_b32_e32 v0, s4
	s_waitcnt vmcnt(0) expcnt(0) lgkmcnt(0)
	ds_read_b32 v2, v0
	s_add_i32 s4, 0, 0x20024
	v_mov_b32_e32 v0, s4
	ds_read_b32 v0, v0
	s_waitcnt lgkmcnt(1)
	v_cmp_ne_u32_e32 vcc, 0, v2
	s_cbranch_vccnz .LBB0_699
	v_readlane_b32 s4, v248, 2
	v_readlane_b32 s5, v248, 3
	v_readlane_b32 s8, v248, 1
	s_mul_i32 s18, s5, s8
	s_mul_i32 s18, s18, s4
	s_add_u32 s4, s94, 0x40200
	s_addc_u32 s5, s95, 0
	s_add_u32 s8, s94, 0x40400
	s_addc_u32 s9, s95, 0
	s_add_u32 s10, s94, 0x40500
	s_addc_u32 s11, s95, 0
	s_add_u32 s38, s94, 0x40600
	s_addc_u32 s39, s95, 0
	s_add_u32 s42, s94, 0x40700
	s_addc_u32 s43, s95, 0
	s_add_u32 s54, s94, 0x40800
	s_addc_u32 s55, s95, 0
	s_add_u32 s56, s94, 0x40900
	s_addc_u32 s57, s95, 0
	s_add_u32 s58, s94, 0x40a00
	s_addc_u32 s59, s95, 0
	s_add_u32 s60, s94, 0x40b00
	s_addc_u32 s61, s95, 0
	s_add_u32 s62, s94, 0x40c00
	s_addc_u32 s63, s95, 0
	s_add_u32 s64, s94, 0x40d00
	s_addc_u32 s65, s95, 0
	s_add_u32 s66, s94, 0x40e00
	s_addc_u32 s67, s95, 0
	s_add_u32 s70, s94, 0x40f00
	s_addc_u32 s71, s95, 0
	s_add_u32 s72, s94, 0x41000
	s_addc_u32 s73, s95, 0
	s_add_u32 s74, s94, 0x41100
	s_addc_u32 s75, s95, 0
	s_add_u32 s34, s94, 0x41200
	s_addc_u32 s35, s95, 0
	s_add_u32 s48, s94, 0x41300
	s_addc_u32 s49, s95, 0
	s_mov_b32 s19, 1
	v_mov_b32_e32 v16, 0
	s_branch .LBB0_687

; __device__ __forceinline__ void xcd_barrier(const XcdBarrier& b) {
;     asm volatile("s_waitcnt vmcnt(0)" ::: "memory");
;     __syncthreads();
;     if (threadIdx.x == 0) {
;         unsigned* bar = b.bar;
;         __builtin_amdgcn_s_waitcnt(0);
;         unsigned nloc = b.st[0], nx = b.st[1];
;         if (nloc == 0u) { xcd_barrier_complete(bar, b.x, nloc, nx); b.st[0] = nloc; b.st[1] = nx; }
.Linv_5:
	s_mov_b64 s[0:1], exec
	v_readlane_b32 s4, v248, 6
	v_readlane_b32 s5, v248, 7
	s_and_b64 s[4:5], s[0:1], s[4:5]
	s_xor_b64 s[0:1], s[4:5], s[0:1]
	s_mov_b64 exec, s[4:5]
	s_cbranch_execz .LBB0_814
	s_add_i32 s4, 0, 0x20020
	v_mov_b32_e32 v0, s4
	s_waitcnt vmcnt(0) expcnt(0) lgkmcnt(0)
	ds_read_b32 v2, v0
	s_add_i32 s4, 0, 0x20024
	v_mov_b32_e32 v0, s4
	ds_read_b32 v0, v0
	s_waitcnt lgkmcnt(1)
	v_cmp_ne_u32_e32 vcc, 0, v2
	s_cbranch_vccnz .LBB0_777
	v_readlane_b32 s4, v248, 2
	v_readlane_b32 s5, v248, 3
	v_readlane_b32 s10, v248, 1
	s_mul_i32 s19, s5, s10
	s_mul_i32 s19, s19, s4
	s_add_u32 s4, s94, 0x40200
	s_addc_u32 s5, s95, 0
	s_add_u32 s10, s94, 0x40400
	s_addc_u32 s11, s95, 0
	s_add_u32 s38, s94, 0x40500
	s_addc_u32 s39, s95, 0
	s_add_u32 s42, s94, 0x40600
	s_addc_u32 s43, s95, 0
	s_add_u32 s52, s94, 0x40700
	s_addc_u32 s53, s95, 0
	s_add_u32 s54, s94, 0x40800
	s_addc_u32 s55, s95, 0
	s_add_u32 s56, s94, 0x40900
	s_addc_u32 s57, s95, 0
	s_add_u32 s58, s94, 0x40a00
	s_addc_u32 s59, s95, 0
	s_add_u32 s60, s94, 0x40b00
	s_addc_u32 s61, s95, 0
	s_add_u32 s62, s94, 0x40c00
	s_addc_u32 s63, s95, 0
	s_add_u32 s64, s94, 0x40d00
	s_addc_u32 s65, s95, 0
	s_add_u32 s66, s94, 0x40e00
	s_addc_u32 s67, s95, 0
	s_add_u32 s70, s94, 0x40f00
	s_addc_u32 s71, s95, 0
	s_add_u32 s72, s94, 0x41000
	s_addc_u32 s73, s95, 0
	s_add_u32 s74, s94, 0x41100
	s_addc_u32 s75, s95, 0
	s_add_u32 s34, s94, 0x41200
	s_addc_u32 s35, s95, 0
	s_add_u32 s48, s94, 0x41300
	s_addc_u32 s49, s95, 0
	s_mov_b32 s21, 1
	v_mov_b32_e32 v16, 0
	s_branch .LBB0_765

; __device__ __forceinline__ unsigned xb_ld(unsigned* p)              { return __hip_atomic_load(p, __ATOMIC_RELAXED, __HIP_MEMORY_SCOPE_AGENT); }
; #define XB_SPIN(cond, bar) do { unsigned _sp = 0; while (cond) { __builtin_amdgcn_s_sleep(1); \
;     if ((++_sp & 255u) == 0u) { if (xb_ld(&(bar)[XB_TMO])) break; if (_sp > XB_SPIN_CAP) { atomicAdd(&(bar)[XB_TMO], 1u); break; } } } } while (0)
; __device__ __forceinline__ void xcd_barrier(const XcdBarrier& b) {
;     ...
;             XB_SPIN(xb_ld(&bar[XB_XGEN(b.x)]) == gen, bar);
;             __builtin_amdgcn_fence(__ATOMIC_ACQUIRE, "agent");
;             asm volatile("s_waitcnt vmcnt(0)" ::: "memory");
.LBB0_792:
	s_or_b64 exec, exec, s[34:35]
	s_waitcnt vmcnt(0)
	s_waitcnt vmcnt(0)

; __device__ __forceinline__ unsigned xb_add(unsigned* p, unsigned v) { return __hip_atomic_fetch_add(p, v, __ATOMIC_RELAXED, __HIP_MEMORY_SCOPE_AGENT); }
; __device__ __forceinline__ void xcd_barrier(const XcdBarrier& b) {
;     ...
;             __builtin_amdgcn_fence(__ATOMIC_ACQUIRE, "agent");
;             xb_add(&bar[XB_XGEN(b.x)], 1u);
.LBB0_810:
	s_or_b64 exec, exec, s[14:15]
	s_mov_b64 s[12:13], exec
	v_mbcnt_lo_u32_b32 v0, s12, 0
	v_mbcnt_hi_u32_b32 v0, s13, v0
	v_cmp_eq_u32_e32 vcc, 0, v0
	s_waitcnt vmcnt(0)
	s_and_saveexec_b64 s[14:15], vcc
	s_cbranch_execz .LBB0_812
	s_bcnt1_i32_b64 s12, s[12:13]

; __device__ __forceinline__ void xcd_barrier(const XcdBarrier& b) {
;     asm volatile("s_waitcnt vmcnt(0)" ::: "memory");
;     __syncthreads();
;     if (threadIdx.x == 0) {
;         unsigned* bar = b.bar;
;         __builtin_amdgcn_s_waitcnt(0);
;         unsigned nloc = b.st[0], nx = b.st[1];
;         if (nloc == 0u) { xcd_barrier_complete(bar, b.x, nloc, nx); b.st[0] = nloc; b.st[1] = nx; }
; __global__ void __launch_bounds__(NTHR, 2) hybrid_block_fwd(Args a) {
;     ...
;         for (int it = gw; it < I_UP + I_DOWN; it += NWV) {
;             if (it < I_UP) {
;                 const int nblk = 2 * FF / 32, kb = it / nblk, nb = it % nblk, n0 = nb * 32, pn = n0 >> 8, bj = (n0 >> 7) & 1, j0 = n0 & 127, k0 = kb * 64;
;                 tr_tile(w_up + (size_t)k0 * (2 * FF) + bj * FF + pn * 128 + j0, 2 * FF, g_mlp + k0, WT_UP + (size_t)n0 * D + k0, D, scr, lane);
;             } else tr_plain(w_down, FF, D, nullptr, WT_DOWN, it - I_UP, scr, lane);
.Lp5_tr_done:
	s_add_u32 s27, s94, 0x10f00000
	s_addc_u32 s28, s95, 0
	s_waitcnt vmcnt(0)
	v_readlane_b32 s72, v248, 6
	v_readlane_b32 s73, v248, 7
	s_waitcnt lgkmcnt(0)
	s_barrier
	v_readfirstlane_b32 s0, v212
	s_cmp_lg_u32 s0, 64
	s_cbranch_scc1 .Linv_6
	buffer_inv sc1
	s_waitcnt vmcnt(0)
.Linv_6:
	s_and_saveexec_b64 s[0:1], s[72:73]
	s_xor_b64 s[0:1], exec, s[0:1]
	s_mov_b64 s[74:75], s[2:3]
	s_cbranch_execz .LBB0_915
	s_add_i32 s4, 0, 0x20020
	v_mov_b32_e32 v0, s4
	s_waitcnt vmcnt(0) expcnt(0) lgkmcnt(0)
	ds_read_b32 v2, v0
	s_add_i32 s4, 0, 0x20024
	v_mov_b32_e32 v0, s4
	ds_read_b32 v0, v0
	s_waitcnt lgkmcnt(1)
	v_cmp_ne_u32_e32 vcc, 0, v2
	s_cbranch_vccnz .LBB0_878
	v_readlane_b32 s4, v248, 2
	v_readlane_b32 s5, v248, 3
	v_readlane_b32 s6, v248, 1
	s_mul_i32 s21, s5, s6
	s_mul_i32 s21, s21, s4
	s_add_u32 s4, s94, 0x40200
	s_addc_u32 s5, s95, 0
	s_add_u32 s6, s94, 0x40400
	s_addc_u32 s7, s95, 0
	s_add_u32 s8, s94, 0x40500
	s_addc_u32 s9, s95, 0
	s_add_u32 s10, s94, 0x40600
	s_addc_u32 s11, s95, 0
	s_add_u32 s16, s94, 0x40700
	s_addc_u32 s17, s95, 0
	s_add_u32 s18, s94, 0x40800
	s_addc_u32 s19, s95, 0
	s_add_u32 s24, s94, 0x40900
	s_addc_u32 s25, s95, 0
	s_add_u32 s38, s94, 0x40a00
	s_addc_u32 s39, s95, 0
	s_add_u32 s42, s94, 0x40b00
	s_addc_u32 s43, s95, 0
	s_add_u32 s50, s94, 0x40c00
	s_addc_u32 s51, s95, 0
	s_add_u32 s52, s94, 0x40d00
	s_addc_u32 s53, s95, 0
	s_add_u32 s54, s94, 0x40e00
	s_addc_u32 s55, s95, 0
	s_add_u32 s56, s94, 0x40f00
	s_addc_u32 s57, s95, 0
	s_add_u32 s58, s94, 0x41000
	s_addc_u32 s59, s95, 0
	s_add_u32 s60, s94, 0x41100
	s_addc_u32 s61, s95, 0
	s_add_u32 s34, s94, 0x41200
	s_addc_u32 s35, s95, 0
	s_add_u32 s48, s94, 0x41300
	s_addc_u32 s49, s95, 0
	s_mov_b32 s22, 1
	v_mov_b32_e32 v16, 0
	s_branch .LBB0_866

; #define PG8_WAIT_V(n) asm volatile("s_waitcnt vmcnt(" #n ")" ::: "memory")
; #define PG8_BAR __builtin_amdgcn_s_barrier()
; __device__ __forceinline__ void xcd_barrier(const XcdBarrier& b) {
;     asm volatile("s_waitcnt vmcnt(0)" ::: "memory");
;     __syncthreads();
;     if (threadIdx.x == 0) {
;         unsigned* bar = b.bar;
;         __builtin_amdgcn_s_waitcnt(0);
;         unsigned nloc = b.st[0], nx = b.st[1];
;         if (nloc == 0u) { xcd_barrier_complete(bar, b.x, nloc, nx); b.st[0] = nloc; b.st[1] = nx; }
; template <class Epi, class Sched>
; __device__ __forceinline__ void gemm_phase(LAS unsigned char* lds, const Gemm g, const Sched& S, const Epi& E) {
;     ...
;     PG8_WAIT_V(0);
;     PG8_BAR;
.LBB0_949:
	s_waitcnt vmcnt(0)
	s_barrier
	s_waitcnt vmcnt(0)
	s_barrier
	v_readfirstlane_b32 s0, v212
	s_cmp_lg_u32 s0, 64
	s_cbranch_scc1 .Linv_7
	buffer_inv sc1
	s_waitcnt vmcnt(0)
.Linv_7:
	s_and_saveexec_b64 s[0:1], s[72:73]
	s_xor_b64 s[0:1], exec, s[0:1]
	s_cbranch_execz .LBB0_1002
	s_add_i32 s4, 0, 0x20020
	v_mov_b32_e32 v0, s4
	s_waitcnt vmcnt(0) expcnt(0) lgkmcnt(0)
	ds_read_b32 v2, v0
	s_add_i32 s4, 0, 0x20024
	v_mov_b32_e32 v0, s4
	ds_read_b32 v0, v0
	s_waitcnt lgkmcnt(1)
	v_cmp_ne_u32_e32 vcc, 0, v2
	s_cbranch_vccnz .LBB0_965
	v_readlane_b32 s4, v248, 2
	v_readlane_b32 s5, v248, 3
	v_readlane_b32 s6, v248, 1
	s_mul_i32 s20, s5, s6
	s_mul_i32 s20, s20, s4
	s_add_u32 s4, s94, 0x40200
	s_addc_u32 s5, s95, 0
	s_add_u32 s6, s94, 0x40400
	s_addc_u32 s7, s95, 0
	s_add_u32 s8, s94, 0x40500
	s_addc_u32 s9, s95, 0
	s_add_u32 s42, s94, 0x40600
	s_addc_u32 s43, s95, 0
	s_add_u32 s44, s94, 0x40700
	s_addc_u32 s45, s95, 0
	s_add_u32 s46, s94, 0x40800
	s_addc_u32 s47, s95, 0
	s_add_u32 s48, s94, 0x40900
	s_addc_u32 s49, s95, 0
	s_add_u32 s50, s94, 0x40a00
	s_addc_u32 s51, s95, 0
	s_add_u32 s52, s94, 0x40b00
	s_addc_u32 s53, s95, 0
	s_add_u32 s54, s94, 0x40c00
	s_addc_u32 s55, s95, 0
	s_add_u32 s56, s94, 0x40d00
	s_addc_u32 s57, s95, 0
	s_add_u32 s58, s94, 0x40e00
	s_addc_u32 s59, s95, 0
	s_add_u32 s60, s94, 0x40f00
	s_addc_u32 s61, s95, 0
	s_add_u32 s62, s94, 0x41000
	s_addc_u32 s63, s95, 0
	s_add_u32 s64, s94, 0x41100
	s_addc_u32 s65, s95, 0
	s_add_u32 s34, s94, 0x41200
	s_addc_u32 s35, s95, 0
	s_add_u32 s66, s94, 0x41300
	s_addc_u32 s67, s95, 0
	s_mov_b32 s21, 1
	v_mov_b32_e32 v16, 0
	s_branch .LBB0_953

; __device__ __forceinline__ unsigned xb_add(unsigned* p, unsigned v) { return __hip_atomic_fetch_add(p, v, __ATOMIC_RELAXED, __HIP_MEMORY_SCOPE_AGENT); }
; __device__ __forceinline__ void xcd_barrier(const XcdBarrier& b) {
;     ...
;             __builtin_amdgcn_fence(__ATOMIC_ACQUIRE, "agent");
;             xb_add(&bar[XB_XGEN(b.x)], 1u);
.LBB0_998:
	s_or_b64 exec, exec, s[8:9]
	s_mov_b64 s[8:9], exec
	v_mbcnt_lo_u32_b32 v0, s8, 0
	v_mbcnt_hi_u32_b32 v0, s9, v0
	v_cmp_eq_u32_e32 vcc, 0, v0
	s_waitcnt vmcnt(0)
	s_and_saveexec_b64 s[12:13], vcc
	s_cbranch_execz .LBB0_1000
	s_bcnt1_i32_b64 s8, s[8:9]

; __device__ __forceinline__ unsigned cvt_pk_bf16(float lo, float hi) { unsigned r; asm volatile("v_cvt_pk_bf16_f32 %0, %1, %2" : "=v"(r) : "v"(lo), "v"(hi)); return r; }
; __global__ void __launch_bounds__(NTHR, 2) hybrid_block_fwd(Args a) {
;     ...
;         for (int idx = gtid; idx < 256 * 2 * (FF / 4); idx += NT) {
;             const int f4 = (idx % (FF / 4)) * 4, rr = (idx / (FF / 4)) & 1, blk = idx / (2 * (FF / 4));
;             const bool seq0 = (blk & 127) == 0; const size_t row = (size_t)blk * 64 + rr;
;             const f32x4 z = (f32x4){0.f, 0.f, 0.f, 0.f};
;             const f32x4 gc = *(const f32x4*)(HEADG + ((size_t)blk * 2 + rr) * FF + f4), vv = *(const f32x4*)(HEADV + ((size_t)blk * 2 + rr) * FF + f4);
;             f32x4 p1, p2;
;             if (rr == 0) { p1 = seq0 ? z : *(const f32x4*)(TAILG + ((size_t)(blk - 1) * 2 + 1) * FF + f4); p2 = seq0 ? z : *(const f32x4*)(TAILG + ((size_t)(blk - 1) * 2 + 0) * FF + f4); }
;             else { p1 = *(const f32x4*)(HEADG + ((size_t)blk * 2 + 0) * FF + f4); p2 = seq0 ? z : *(const f32x4*)(TAILG + ((size_t)(blk - 1) * 2 + 1) * FF + f4); }
;             const f32x4 cv = *(const f32x4*)(ffn_conv_b + f4) + *(const f32x4*)(ffn_conv_w + f4) * p2 + *(const f32x4*)(ffn_conv_w + FF + f4) * p1 + *(const f32x4*)(ffn_conv_w + 2 * FF + f4) * gc;
;             u32x2 w; w.x = cvt_pk_bf16(gelu_tanh(cv[0]) * vv[0], gelu_tanh(cv[1]) * vv[1]); w.y = cvt_pk_bf16(gelu_tanh(cv[2]) * vv[2], gelu_tanh(cv[3]) * vv[3]);
;             *(u32x2*)(ACT + row * FF + f4) = w;
.LBB0_1002:
	s_or_b64 exec, exec, s[0:1]
	s_waitcnt lgkmcnt(0)
	v_mov_b32_e32 v0, v212
	v_readlane_b32 s0, v248, 8
	s_barrier
	s_mov_b64 s[4:5], exec
	v_add_u32_e32 v1, s0, v0
	s_mov_b32 s6, 0x2aaaaaab
	v_mul_hi_i32 v2, v1, s6
	v_ashrrev_i32_e32 v3, 8, v2
	v_lshlrev_b32_e32 v4, 4, v1
	v_mul_u32_u24_e32 v5, 0x6000, v3
	v_sub_u32_e32 v4, v4, v5
	v_mov_b32_e32 v49, v3
	v_add_u32_e32 v6, v5, v4
	v_add_u32_e32 v7, 0x2700000, v6
	global_load_dwordx4 v[16:19], v7, s[94:95]
	v_add_u32_e32 v7, 0x3300000, v6
	global_load_dwordx4 v[20:23], v7, s[94:95]
	v_and_b32_e32 v8, 1, v3
	v_max_i32_e32 v9, 1, v3
	v_add_u32_e32 v9, -1, v9
	v_mul_u32_u24_e32 v9, 0x6000, v9
	v_add_u32_e32 v9, v9, v4
	v_cmp_eq_u32_e32 vcc, 1, v8
	v_mov_b32_e32 v7, 0x1b00000
	v_mov_b32_e32 v5, 0x2700000
	v_cndmask_b32_e32 v7, v7, v5, vcc
	v_add_u32_e32 v7, v7, v9
	global_load_dwordx4 v[24:27], v7, s[94:95]
	v_max_i32_e32 v9, 2, v3
	v_add_u32_e32 v9, -2, v9
	v_mul_u32_u24_e32 v9, 0x6000, v9
	v_add_u32_e32 v9, v9, v4
	v_add_u32_e32 v9, 0x1b00000, v9
	global_load_dwordx4 v[28:31], v9, s[94:95]
	global_load_dwordx4 v[32:35], v4, s[86:87]
	global_load_dwordx4 v[36:39], v4, s[84:85]
	global_load_dwordx4 v[40:43], v4, s[16:17]
	global_load_dwordx4 v[44:47], v4, s[18:19]
	v_lshrrev_b32_e32 v5, 1, v3
	v_lshl_or_b32 v5, v5, 6, v8
	v_mul_u32_u24_e32 v5, 0x3000, v5
	v_lshrrev_b32_e32 v7, 1, v4
	v_add_u32_e32 v5, v5, v7
	v_add_u32_e32 v48, 0x12700000, v5
	v_add_u32_e32 v1, 0x20000, v1
	v_mul_hi_i32 v2, v1, s6
	v_ashrrev_i32_e32 v3, 8, v2
	v_lshlrev_b32_e32 v4, 4, v1
	v_mul_u32_u24_e32 v5, 0x6000, v3
	v_sub_u32_e32 v4, v4, v5
	v_mov_b32_e32 v85, v3
	v_add_u32_e32 v6, v5, v4
	v_add_u32_e32 v7, 0x2700000, v6
	global_load_dwordx4 v[52:55], v7, s[94:95]
	v_add_u32_e32 v7, 0x3300000, v6
	global_load_dwordx4 v[56:59], v7, s[94:95]
	v_and_b32_e32 v8, 1, v3
	v_max_i32_e32 v9, 1, v3
	v_add_u32_e32 v9, -1, v9
	v_mul_u32_u24_e32 v9, 0x6000, v9
	v_add_u32_e32 v9, v9, v4
	v_cmp_eq_u32_e32 vcc, 1, v8
	v_mov_b32_e32 v7, 0x1b00000
	v_mov_b32_e32 v5, 0x2700000
	v_cndmask_b32_e32 v7, v7, v5, vcc
	v_add_u32_e32 v7, v7, v9
	global_load_dwordx4 v[60:63], v7, s[94:95]
	v_max_i32_e32 v9, 2, v3
	v_add_u32_e32 v9, -2, v9
	v_mul_u32_u24_e32 v9, 0x6000, v9
	v_add_u32_e32 v9, v9, v4
	v_add_u32_e32 v9, 0x1b00000, v9
	global_load_dwordx4 v[64:67], v9, s[94:95]
	global_load_dwordx4 v[68:71], v4, s[86:87]
	global_load_dwordx4 v[72:75], v4, s[84:85]
	global_load_dwordx4 v[76:79], v4, s[16:17]
	global_load_dwordx4 v[80:83], v4, s[18:19]
	v_lshrrev_b32_e32 v5, 1, v3
	v_lshl_or_b32 v5, v5, 6, v8
	v_mul_u32_u24_e32 v5, 0x3000, v5
	v_lshrrev_b32_e32 v7, 1, v4
	v_add_u32_e32 v5, v5, v7
	v_add_u32_e32 v84, 0x12700000, v5
	v_add_u32_e32 v1, 0x20000, v1
	v_mul_hi_i32 v2, v1, s6
	v_ashrrev_i32_e32 v3, 8, v2
	v_lshlrev_b32_e32 v4, 4, v1
	v_mul_u32_u24_e32 v5, 0x6000, v3
	v_sub_u32_e32 v4, v4, v5
	v_mov_b32_e32 v121, v3
	v_add_u32_e32 v6, v5, v4
	v_add_u32_e32 v7, 0x2700000, v6
	global_load_dwordx4 v[88:91], v7, s[94:95]
	v_add_u32_e32 v7, 0x3300000, v6
	global_load_dwordx4 v[92:95], v7, s[94:95]
	v_and_b32_e32 v8, 1, v3
	v_max_i32_e32 v9, 1, v3
	v_add_u32_e32 v9, -1, v9
	v_mul_u32_u24_e32 v9, 0x6000, v9
	v_add_u32_e32 v9, v9, v4
	v_cmp_eq_u32_e32 vcc, 1, v8
	v_mov_b32_e32 v7, 0x1b00000
	v_mov_b32_e32 v5, 0x2700000
	v_cndmask_b32_e32 v7, v7, v5, vcc
	v_add_u32_e32 v7, v7, v9
	global_load_dwordx4 v[96:99], v7, s[94:95]
	v_max_i32_e32 v9, 2, v3
	v_add_u32_e32 v9, -2, v9
	v_mul_u32_u24_e32 v9, 0x6000, v9
	v_add_u32_e32 v9, v9, v4
	v_add_u32_e32 v9, 0x1b00000, v9
	global_load_dwordx4 v[100:103], v9, s[94:95]
	global_load_dwordx4 v[104:107], v4, s[86:87]
	global_load_dwordx4 v[108:111], v4, s[84:85]
	global_load_dwordx4 v[112:115], v4, s[16:17]
	global_load_dwordx4 v[116:119], v4, s[18:19]
	v_lshrrev_b32_e32 v5, 1, v3
	v_lshl_or_b32 v5, v5, 6, v8
	v_mul_u32_u24_e32 v5, 0x3000, v5
	v_lshrrev_b32_e32 v7, 1, v4
	v_add_u32_e32 v5, v5, v7
	v_add_u32_e32 v120, 0x12700000, v5
	v_add_u32_e32 v1, 0x20000, v1
	s_waitcnt vmcnt(16)
	v_lshrrev_b32_e32 v2, 1, v49
	v_and_b32_e32 v2, 0x7f, v2
	v_cmp_eq_u32_e32 vcc, 0, v2
	v_and_b32_e32 v3, 1, v49
	v_cmp_eq_u32_e64 s[8:9], 0, v3
	s_nop 1
	s_and_b64 s[8:9], s[8:9], vcc
	s_nop 1
	v_cndmask_b32_e64 v28, v28, 0, vcc
	v_cndmask_b32_e64 v24, v24, 0, s[8:9]
	v_cndmask_b32_e64 v29, v29, 0, vcc
	v_cndmask_b32_e64 v25, v25, 0, s[8:9]
	v_cndmask_b32_e64 v30, v30, 0, vcc
	v_cndmask_b32_e64 v26, v26, 0, s[8:9]
	v_cndmask_b32_e64 v31, v31, 0, vcc
	v_cndmask_b32_e64 v27, v27, 0, s[8:9]
	v_pk_fma_f32 v[30:31], v[30:31], v[38:39], v[34:35]
	v_pk_fma_f32 v[28:29], v[28:29], v[36:37], v[32:33]
	v_pk_fma_f32 v[26:27], v[26:27], v[42:43], v[30:31]
	v_pk_fma_f32 v[24:25], v[24:25], v[40:41], v[28:29]
	v_pk_fma_f32 v[18:19], v[18:19], v[46:47], v[26:27]
	v_pk_fma_f32 v[16:17], v[16:17], v[44:45], v[24:25]
	v_mul_f32_e32 v32, 0x3d922279, v16
	v_mul_f32_e32 v33, 0x3d922279, v17
	v_mul_f32_e32 v34, 0x3d922279, v18
	v_mul_f32_e32 v35, 0x3d922279, v19
	v_fmaak_f32 v32, v16, v32, 0x3fcc422a
	v_fmaak_f32 v33, v17, v33, 0x3fcc422a
	v_fmaak_f32 v34, v18, v34, 0x3fcc422a
	v_fmaak_f32 v35, v19, v35, 0x3fcc422a
	v_mul_f32_e32 v32, v16, v32
	v_mul_f32_e32 v33, v17, v33
	v_mul_f32_e32 v34, v18, v34
	v_mul_f32_e32 v35, v19, v35
	v_mul_f32_e32 v32, 0xbfb8aa3b, v32
	v_mul_f32_e32 v33, 0xbfb8aa3b, v33
	v_mul_f32_e32 v34, 0xbfb8aa3b, v34
	v_mul_f32_e32 v35, 0xbfb8aa3b, v35
	v_exp_f32_e32 v32, v32
	v_exp_f32_e32 v33, v33
	v_exp_f32_e32 v34, v34
	v_exp_f32_e32 v35, v35
	v_add_f32_e32 v32, 1.0, v32
	v_add_f32_e32 v33, 1.0, v33
	v_add_f32_e32 v34, 1.0, v34
	v_add_f32_e32 v35, 1.0, v35
	v_rcp_f32_e32 v32, v32
	v_rcp_f32_e32 v33, v33
	v_rcp_f32_e32 v34, v34
	v_rcp_f32_e32 v35, v35
	v_mul_f32_e32 v16, v16, v32
	v_mul_f32_e32 v17, v17, v33
	v_mul_f32_e32 v18, v18, v34
	v_mul_f32_e32 v19, v19, v35
	v_mul_f32_e32 v16, v20, v16
	v_mul_f32_e32 v17, v21, v17
	v_mul_f32_e32 v18, v22, v18
	v_mul_f32_e32 v19, v23, v19
	v_cvt_pk_bf16_f32 v16, v16, v17
	v_cvt_pk_bf16_f32 v17, v18, v19
	global_store_dwordx2 v48, v[16:17], s[94:95]
	s_waitcnt vmcnt(9)
; __device__ __forceinline__ unsigned cvt_pk_bf16(float lo, float hi) { unsigned r; asm volatile("v_cvt_pk_bf16_f32 %0, %1, %2" : "=v"(r) : "v"(lo), "v"(hi)); return r; }
; __global__ void __launch_bounds__(NTHR, 2) hybrid_block_fwd(Args a) {
;     ...
;         for (int idx = gtid; idx < 256 * 2 * (FF / 4); idx += NT) {
;             const int f4 = (idx % (FF / 4)) * 4, rr = (idx / (FF / 4)) & 1, blk = idx / (2 * (FF / 4));
;             const bool seq0 = (blk & 127) == 0; const size_t row = (size_t)blk * 64 + rr;
;             const f32x4 z = (f32x4){0.f, 0.f, 0.f, 0.f};
;             const f32x4 gc = *(const f32x4*)(HEADG + ((size_t)blk * 2 + rr) * FF + f4), vv = *(const f32x4*)(HEADV + ((size_t)blk * 2 + rr) * FF + f4);
;             f32x4 p1, p2;
;             if (rr == 0) { p1 = seq0 ? z : *(const f32x4*)(TAILG + ((size_t)(blk - 1) * 2 + 1) * FF + f4); p2 = seq0 ? z : *(const f32x4*)(TAILG + ((size_t)(blk - 1) * 2 + 0) * FF + f4); }
;             else { p1 = *(const f32x4*)(HEADG + ((size_t)blk * 2 + 0) * FF + f4); p2 = seq0 ? z : *(const f32x4*)(TAILG + ((size_t)(blk - 1) * 2 + 1) * FF + f4); }
;             const f32x4 cv = *(const f32x4*)(ffn_conv_b + f4) + *(const f32x4*)(ffn_conv_w + f4) * p2 + *(const f32x4*)(ffn_conv_w + FF + f4) * p1 + *(const f32x4*)(ffn_conv_w + 2 * FF + f4) * gc;
;             u32x2 w; w.x = cvt_pk_bf16(gelu_tanh(cv[0]) * vv[0], gelu_tanh(cv[1]) * vv[1]); w.y = cvt_pk_bf16(gelu_tanh(cv[2]) * vv[2], gelu_tanh(cv[3]) * vv[3]);
;             *(u32x2*)(ACT + row * FF + f4) = w;
	v_lshrrev_b32_e32 v2, 1, v85
	v_and_b32_e32 v2, 0x7f, v2
	v_cmp_eq_u32_e32 vcc, 0, v2
	v_and_b32_e32 v3, 1, v85
	v_cmp_eq_u32_e64 s[8:9], 0, v3
	s_nop 1
	s_and_b64 s[8:9], s[8:9], vcc
	s_nop 1
	v_cndmask_b32_e64 v64, v64, 0, vcc
	v_cndmask_b32_e64 v60, v60, 0, s[8:9]
	v_cndmask_b32_e64 v65, v65, 0, vcc
	v_cndmask_b32_e64 v61, v61, 0, s[8:9]
	v_cndmask_b32_e64 v66, v66, 0, vcc
	v_cndmask_b32_e64 v62, v62, 0, s[8:9]
	v_cndmask_b32_e64 v67, v67, 0, vcc
	v_cndmask_b32_e64 v63, v63, 0, s[8:9]
	v_pk_fma_f32 v[66:67], v[66:67], v[74:75], v[70:71]
	v_pk_fma_f32 v[64:65], v[64:65], v[72:73], v[68:69]
	v_pk_fma_f32 v[62:63], v[62:63], v[78:79], v[66:67]
	v_pk_fma_f32 v[60:61], v[60:61], v[76:77], v[64:65]
	v_pk_fma_f32 v[54:55], v[54:55], v[82:83], v[62:63]
	v_pk_fma_f32 v[52:53], v[52:53], v[80:81], v[60:61]
	v_mul_f32_e32 v68, 0x3d922279, v52
	v_mul_f32_e32 v69, 0x3d922279, v53
	v_mul_f32_e32 v70, 0x3d922279, v54
	v_mul_f32_e32 v71, 0x3d922279, v55
	v_fmaak_f32 v68, v52, v68, 0x3fcc422a
	v_fmaak_f32 v69, v53, v69, 0x3fcc422a
	v_fmaak_f32 v70, v54, v70, 0x3fcc422a
	v_fmaak_f32 v71, v55, v71, 0x3fcc422a
	v_mul_f32_e32 v68, v52, v68
	v_mul_f32_e32 v69, v53, v69
	v_mul_f32_e32 v70, v54, v70
	v_mul_f32_e32 v71, v55, v71
	v_mul_f32_e32 v68, 0xbfb8aa3b, v68
	v_mul_f32_e32 v69, 0xbfb8aa3b, v69
	v_mul_f32_e32 v70, 0xbfb8aa3b, v70
	v_mul_f32_e32 v71, 0xbfb8aa3b, v71
	v_exp_f32_e32 v68, v68
	v_exp_f32_e32 v69, v69
	v_exp_f32_e32 v70, v70
	v_exp_f32_e32 v71, v71
	v_add_f32_e32 v68, 1.0, v68
	v_add_f32_e32 v69, 1.0, v69
	v_add_f32_e32 v70, 1.0, v70
	v_add_f32_e32 v71, 1.0, v71
	v_rcp_f32_e32 v68, v68
	v_rcp_f32_e32 v69, v69
	v_rcp_f32_e32 v70, v70
	v_rcp_f32_e32 v71, v71
	v_mul_f32_e32 v52, v52, v68
	v_mul_f32_e32 v53, v53, v69
	v_mul_f32_e32 v54, v54, v70
	v_mul_f32_e32 v55, v55, v71
	v_mul_f32_e32 v52, v56, v52
	v_mul_f32_e32 v53, v57, v53
	v_mul_f32_e32 v54, v58, v54
	v_mul_f32_e32 v55, v59, v55
	v_cvt_pk_bf16_f32 v52, v52, v53
	v_cvt_pk_bf16_f32 v53, v54, v55
	global_store_dwordx2 v84, v[52:53], s[94:95]
	s_waitcnt vmcnt(2)
	v_lshrrev_b32_e32 v2, 1, v121
	v_and_b32_e32 v2, 0x7f, v2
	v_cmp_eq_u32_e32 vcc, 0, v2
	v_and_b32_e32 v3, 1, v121
	v_cmp_eq_u32_e64 s[8:9], 0, v3
	s_nop 1
	s_and_b64 s[8:9], s[8:9], vcc
	s_nop 1
	v_cndmask_b32_e64 v100, v100, 0, vcc
	v_cndmask_b32_e64 v96, v96, 0, s[8:9]
	v_cndmask_b32_e64 v101, v101, 0, vcc
	v_cndmask_b32_e64 v97, v97, 0, s[8:9]
	v_cndmask_b32_e64 v102, v102, 0, vcc
	v_cndmask_b32_e64 v98, v98, 0, s[8:9]
	v_cndmask_b32_e64 v103, v103, 0, vcc
	v_cndmask_b32_e64 v99, v99, 0, s[8:9]
	v_pk_fma_f32 v[102:103], v[102:103], v[110:111], v[106:107]
	v_pk_fma_f32 v[100:101], v[100:101], v[108:109], v[104:105]
	v_pk_fma_f32 v[98:99], v[98:99], v[114:115], v[102:103]
	v_pk_fma_f32 v[96:97], v[96:97], v[112:113], v[100:101]
	v_pk_fma_f32 v[90:91], v[90:91], v[118:119], v[98:99]
	v_pk_fma_f32 v[88:89], v[88:89], v[116:117], v[96:97]
	v_mul_f32_e32 v104, 0x3d922279, v88
	v_mul_f32_e32 v105, 0x3d922279, v89
	v_mul_f32_e32 v106, 0x3d922279, v90
	v_mul_f32_e32 v107, 0x3d922279, v91
	v_fmaak_f32 v104, v88, v104, 0x3fcc422a
	v_fmaak_f32 v105, v89, v105, 0x3fcc422a
	v_fmaak_f32 v106, v90, v106, 0x3fcc422a
	v_fmaak_f32 v107, v91, v107, 0x3fcc422a
	v_mul_f32_e32 v104, v88, v104
	v_mul_f32_e32 v105, v89, v105
	v_mul_f32_e32 v106, v90, v106
	v_mul_f32_e32 v107, v91, v107
	v_mul_f32_e32 v104, 0xbfb8aa3b, v104
	v_mul_f32_e32 v105, 0xbfb8aa3b, v105
	v_mul_f32_e32 v106, 0xbfb8aa3b, v106
	v_mul_f32_e32 v107, 0xbfb8aa3b, v107
	v_exp_f32_e32 v104, v104
	v_exp_f32_e32 v105, v105
	v_exp_f32_e32 v106, v106
	v_exp_f32_e32 v107, v107
	v_add_f32_e32 v104, 1.0, v104
	v_add_f32_e32 v105, 1.0, v105
	v_add_f32_e32 v106, 1.0, v106
	v_add_f32_e32 v107, 1.0, v107
	v_rcp_f32_e32 v104, v104
	v_rcp_f32_e32 v105, v105
	v_rcp_f32_e32 v106, v106
	v_rcp_f32_e32 v107, v107
	v_mul_f32_e32 v88, v88, v104
	v_mul_f32_e32 v89, v89, v105
	v_mul_f32_e32 v90, v90, v106
	v_mul_f32_e32 v91, v91, v107
	v_mul_f32_e32 v88, v92, v88
	v_mul_f32_e32 v89, v93, v89
	v_mul_f32_e32 v90, v94, v90
	v_mul_f32_e32 v91, v95, v91
	v_cvt_pk_bf16_f32 v88, v88, v89
	v_cvt_pk_bf16_f32 v89, v90, v91
	global_store_dwordx2 v120, v[88:89], s[94:95]
	v_mul_hi_i32 v2, v1, s6
	v_ashrrev_i32_e32 v3, 8, v2
	v_lshlrev_b32_e32 v4, 4, v1
	v_mul_u32_u24_e32 v5, 0x6000, v3
	v_sub_u32_e32 v4, v4, v5
	v_mov_b32_e32 v49, v3
	v_add_u32_e32 v6, v5, v4
	v_add_u32_e32 v7, 0x2700000, v6
	global_load_dwordx4 v[16:19], v7, s[94:95]
	v_add_u32_e32 v7, 0x3300000, v6
	global_load_dwordx4 v[20:23], v7, s[94:95]
	v_and_b32_e32 v8, 1, v3
	v_max_i32_e32 v9, 1, v3
	v_add_u32_e32 v9, -1, v9
	v_mul_u32_u24_e32 v9, 0x6000, v9
	v_add_u32_e32 v9, v9, v4
	v_cmp_eq_u32_e32 vcc, 1, v8
	v_mov_b32_e32 v7, 0x1b00000
	v_mov_b32_e32 v5, 0x2700000
	v_cndmask_b32_e32 v7, v7, v5, vcc
	v_add_u32_e32 v7, v7, v9
	global_load_dwordx4 v[24:27], v7, s[94:95]
	v_max_i32_e32 v9, 2, v3
	v_add_u32_e32 v9, -2, v9
	v_mul_u32_u24_e32 v9, 0x6000, v9
	v_add_u32_e32 v9, v9, v4
	v_add_u32_e32 v9, 0x1b00000, v9
	global_load_dwordx4 v[28:31], v9, s[94:95]
	global_load_dwordx4 v[32:35], v4, s[86:87]
	global_load_dwordx4 v[36:39], v4, s[84:85]
	global_load_dwordx4 v[40:43], v4, s[16:17]
	global_load_dwordx4 v[44:47], v4, s[18:19]
	v_lshrrev_b32_e32 v5, 1, v3
	v_lshl_or_b32 v5, v5, 6, v8
	v_mul_u32_u24_e32 v5, 0x3000, v5
	v_lshrrev_b32_e32 v7, 1, v4
	v_add_u32_e32 v5, v5, v7
	v_add_u32_e32 v48, 0x12700000, v5
	v_add_u32_e32 v1, 0x20000, v1
	v_mul_hi_i32 v2, v1, s6
	v_ashrrev_i32_e32 v3, 8, v2
	v_lshlrev_b32_e32 v4, 4, v1
	v_mul_u32_u24_e32 v5, 0x6000, v3
	v_sub_u32_e32 v4, v4, v5
	v_mov_b32_e32 v85, v3
	v_add_u32_e32 v6, v5, v4
	v_add_u32_e32 v7, 0x2700000, v6
; __device__ __forceinline__ unsigned cvt_pk_bf16(float lo, float hi) { unsigned r; asm volatile("v_cvt_pk_bf16_f32 %0, %1, %2" : "=v"(r) : "v"(lo), "v"(hi)); return r; }
; __global__ void __launch_bounds__(NTHR, 2) hybrid_block_fwd(Args a) {
;     ...
;         for (int idx = gtid; idx < 256 * 2 * (FF / 4); idx += NT) {
;             const int f4 = (idx % (FF / 4)) * 4, rr = (idx / (FF / 4)) & 1, blk = idx / (2 * (FF / 4));
;             const bool seq0 = (blk & 127) == 0; const size_t row = (size_t)blk * 64 + rr;
;             const f32x4 z = (f32x4){0.f, 0.f, 0.f, 0.f};
;             const f32x4 gc = *(const f32x4*)(HEADG + ((size_t)blk * 2 + rr) * FF + f4), vv = *(const f32x4*)(HEADV + ((size_t)blk * 2 + rr) * FF + f4);
;             f32x4 p1, p2;
;             if (rr == 0) { p1 = seq0 ? z : *(const f32x4*)(TAILG + ((size_t)(blk - 1) * 2 + 1) * FF + f4); p2 = seq0 ? z : *(const f32x4*)(TAILG + ((size_t)(blk - 1) * 2 + 0) * FF + f4); }
;             else { p1 = *(const f32x4*)(HEADG + ((size_t)blk * 2 + 0) * FF + f4); p2 = seq0 ? z : *(const f32x4*)(TAILG + ((size_t)(blk - 1) * 2 + 1) * FF + f4); }
;             const f32x4 cv = *(const f32x4*)(ffn_conv_b + f4) + *(const f32x4*)(ffn_conv_w + f4) * p2 + *(const f32x4*)(ffn_conv_w + FF + f4) * p1 + *(const f32x4*)(ffn_conv_w + 2 * FF + f4) * gc;
;             u32x2 w; w.x = cvt_pk_bf16(gelu_tanh(cv[0]) * vv[0], gelu_tanh(cv[1]) * vv[1]); w.y = cvt_pk_bf16(gelu_tanh(cv[2]) * vv[2], gelu_tanh(cv[3]) * vv[3]);
;             *(u32x2*)(ACT + row * FF + f4) = w;
	global_load_dwordx4 v[52:55], v7, s[94:95]
	v_add_u32_e32 v7, 0x3300000, v6
	global_load_dwordx4 v[56:59], v7, s[94:95]
	v_and_b32_e32 v8, 1, v3
	v_max_i32_e32 v9, 1, v3
	v_add_u32_e32 v9, -1, v9
	v_mul_u32_u24_e32 v9, 0x6000, v9
	v_add_u32_e32 v9, v9, v4
	v_cmp_eq_u32_e32 vcc, 1, v8
	v_mov_b32_e32 v7, 0x1b00000
	v_mov_b32_e32 v5, 0x2700000
	v_cndmask_b32_e32 v7, v7, v5, vcc
	v_add_u32_e32 v7, v7, v9
	global_load_dwordx4 v[60:63], v7, s[94:95]
	v_max_i32_e32 v9, 2, v3
	v_add_u32_e32 v9, -2, v9
	v_mul_u32_u24_e32 v9, 0x6000, v9
	v_add_u32_e32 v9, v9, v4
	v_add_u32_e32 v9, 0x1b00000, v9
	global_load_dwordx4 v[64:67], v9, s[94:95]
	global_load_dwordx4 v[68:71], v4, s[86:87]
	global_load_dwordx4 v[72:75], v4, s[84:85]
	global_load_dwordx4 v[76:79], v4, s[16:17]
	global_load_dwordx4 v[80:83], v4, s[18:19]
	v_lshrrev_b32_e32 v5, 1, v3
	v_lshl_or_b32 v5, v5, 6, v8
	v_mul_u32_u24_e32 v5, 0x3000, v5
	v_lshrrev_b32_e32 v7, 1, v4
	v_add_u32_e32 v5, v5, v7
	v_add_u32_e32 v84, 0x12700000, v5
	v_add_u32_e32 v1, 0x20000, v1
	v_mul_hi_i32 v2, v1, s6
	v_ashrrev_i32_e32 v3, 8, v2
	v_lshlrev_b32_e32 v4, 4, v1
	v_mul_u32_u24_e32 v5, 0x6000, v3
	v_sub_u32_e32 v4, v4, v5
	v_mov_b32_e32 v121, v3
	v_add_u32_e32 v6, v5, v4
	v_add_u32_e32 v7, 0x2700000, v6
	global_load_dwordx4 v[88:91], v7, s[94:95]
	v_add_u32_e32 v7, 0x3300000, v6
	global_load_dwordx4 v[92:95], v7, s[94:95]
	v_and_b32_e32 v8, 1, v3
	v_max_i32_e32 v9, 1, v3
	v_add_u32_e32 v9, -1, v9
	v_mul_u32_u24_e32 v9, 0x6000, v9
	v_add_u32_e32 v9, v9, v4
	v_cmp_eq_u32_e32 vcc, 1, v8
	v_mov_b32_e32 v7, 0x1b00000
	v_mov_b32_e32 v5, 0x2700000
	v_cndmask_b32_e32 v7, v7, v5, vcc
	v_add_u32_e32 v7, v7, v9
	global_load_dwordx4 v[96:99], v7, s[94:95]
	v_max_i32_e32 v9, 2, v3
	v_add_u32_e32 v9, -2, v9
	v_mul_u32_u24_e32 v9, 0x6000, v9
	v_add_u32_e32 v9, v9, v4
	v_add_u32_e32 v9, 0x1b00000, v9
	global_load_dwordx4 v[100:103], v9, s[94:95]
	global_load_dwordx4 v[104:107], v4, s[86:87]
	global_load_dwordx4 v[108:111], v4, s[84:85]
	global_load_dwordx4 v[112:115], v4, s[16:17]
	global_load_dwordx4 v[116:119], v4, s[18:19]
	v_lshrrev_b32_e32 v5, 1, v3
	v_lshl_or_b32 v5, v5, 6, v8
	v_mul_u32_u24_e32 v5, 0x3000, v5
	v_lshrrev_b32_e32 v7, 1, v4
	v_add_u32_e32 v5, v5, v7
	v_add_u32_e32 v120, 0x12700000, v5
	v_add_u32_e32 v1, 0x20000, v1
	s_waitcnt vmcnt(16)
	v_lshrrev_b32_e32 v2, 1, v49
	v_and_b32_e32 v2, 0x7f, v2
	v_cmp_eq_u32_e32 vcc, 0, v2
	v_and_b32_e32 v3, 1, v49
	v_cmp_eq_u32_e64 s[8:9], 0, v3
	s_nop 1
	s_and_b64 s[8:9], s[8:9], vcc
	s_nop 1
	v_cndmask_b32_e64 v28, v28, 0, vcc
	v_cndmask_b32_e64 v24, v24, 0, s[8:9]
	v_cndmask_b32_e64 v29, v29, 0, vcc
	v_cndmask_b32_e64 v25, v25, 0, s[8:9]
	v_cndmask_b32_e64 v30, v30, 0, vcc
	v_cndmask_b32_e64 v26, v26, 0, s[8:9]
	v_cndmask_b32_e64 v31, v31, 0, vcc
	v_cndmask_b32_e64 v27, v27, 0, s[8:9]
	v_pk_fma_f32 v[30:31], v[30:31], v[38:39], v[34:35]
	v_pk_fma_f32 v[28:29], v[28:29], v[36:37], v[32:33]
	v_pk_fma_f32 v[26:27], v[26:27], v[42:43], v[30:31]
	v_pk_fma_f32 v[24:25], v[24:25], v[40:41], v[28:29]
	v_pk_fma_f32 v[18:19], v[18:19], v[46:47], v[26:27]
	v_pk_fma_f32 v[16:17], v[16:17], v[44:45], v[24:25]
	v_mul_f32_e32 v32, 0x3d922279, v16
	v_mul_f32_e32 v33, 0x3d922279, v17
	v_mul_f32_e32 v34, 0x3d922279, v18
	v_mul_f32_e32 v35, 0x3d922279, v19
	v_fmaak_f32 v32, v16, v32, 0x3fcc422a
	v_fmaak_f32 v33, v17, v33, 0x3fcc422a
	v_fmaak_f32 v34, v18, v34, 0x3fcc422a
	v_fmaak_f32 v35, v19, v35, 0x3fcc422a
	v_mul_f32_e32 v32, v16, v32
	v_mul_f32_e32 v33, v17, v33
	v_mul_f32_e32 v34, v18, v34
	v_mul_f32_e32 v35, v19, v35
	v_mul_f32_e32 v32, 0xbfb8aa3b, v32
	v_mul_f32_e32 v33, 0xbfb8aa3b, v33
	v_mul_f32_e32 v34, 0xbfb8aa3b, v34
	v_mul_f32_e32 v35, 0xbfb8aa3b, v35
	v_exp_f32_e32 v32, v32
	v_exp_f32_e32 v33, v33
	v_exp_f32_e32 v34, v34
	v_exp_f32_e32 v35, v35
	v_add_f32_e32 v32, 1.0, v32
	v_add_f32_e32 v33, 1.0, v33
	v_add_f32_e32 v34, 1.0, v34
	v_add_f32_e32 v35, 1.0, v35
	v_rcp_f32_e32 v32, v32
	v_rcp_f32_e32 v33, v33
	v_rcp_f32_e32 v34, v34
	v_rcp_f32_e32 v35, v35
	v_mul_f32_e32 v16, v16, v32
	v_mul_f32_e32 v17, v17, v33
	v_mul_f32_e32 v18, v18, v34
	v_mul_f32_e32 v19, v19, v35
	v_mul_f32_e32 v16, v20, v16
	v_mul_f32_e32 v17, v21, v17
	v_mul_f32_e32 v18, v22, v18
	v_mul_f32_e32 v19, v23, v19
	v_cvt_pk_bf16_f32 v16, v16, v17
	v_cvt_pk_bf16_f32 v17, v18, v19
	global_store_dwordx2 v48, v[16:17], s[94:95]
	s_waitcnt vmcnt(9)
; __device__ __forceinline__ unsigned cvt_pk_bf16(float lo, float hi) { unsigned r; asm volatile("v_cvt_pk_bf16_f32 %0, %1, %2" : "=v"(r) : "v"(lo), "v"(hi)); return r; }
; __device__ __forceinline__ void xcd_barrier(const XcdBarrier& b) {
;     asm volatile("s_waitcnt vmcnt(0)" ::: "memory");
;     __syncthreads();
;     if (threadIdx.x == 0) {
;         unsigned* bar = b.bar;
;         __builtin_amdgcn_s_waitcnt(0);
;         unsigned nloc = b.st[0], nx = b.st[1];
;         if (nloc == 0u) { xcd_barrier_complete(bar, b.x, nloc, nx); b.st[0] = nloc; b.st[1] = nx; }
; __global__ void __launch_bounds__(NTHR, 2) hybrid_block_fwd(Args a) {
;     ...
;         for (int idx = gtid; idx < 256 * 2 * (FF / 4); idx += NT) {
;             const int f4 = (idx % (FF / 4)) * 4, rr = (idx / (FF / 4)) & 1, blk = idx / (2 * (FF / 4));
;             const bool seq0 = (blk & 127) == 0; const size_t row = (size_t)blk * 64 + rr;
;             const f32x4 z = (f32x4){0.f, 0.f, 0.f, 0.f};
;             const f32x4 gc = *(const f32x4*)(HEADG + ((size_t)blk * 2 + rr) * FF + f4), vv = *(const f32x4*)(HEADV + ((size_t)blk * 2 + rr) * FF + f4);
;             f32x4 p1, p2;
;             if (rr == 0) { p1 = seq0 ? z : *(const f32x4*)(TAILG + ((size_t)(blk - 1) * 2 + 1) * FF + f4); p2 = seq0 ? z : *(const f32x4*)(TAILG + ((size_t)(blk - 1) * 2 + 0) * FF + f4); }
;             else { p1 = *(const f32x4*)(HEADG + ((size_t)blk * 2 + 0) * FF + f4); p2 = seq0 ? z : *(const f32x4*)(TAILG + ((size_t)(blk - 1) * 2 + 1) * FF + f4); }
;             const f32x4 cv = *(const f32x4*)(ffn_conv_b + f4) + *(const f32x4*)(ffn_conv_w + f4) * p2 + *(const f32x4*)(ffn_conv_w + FF + f4) * p1 + *(const f32x4*)(ffn_conv_w + 2 * FF + f4) * gc;
;             u32x2 w; w.x = cvt_pk_bf16(gelu_tanh(cv[0]) * vv[0], gelu_tanh(cv[1]) * vv[1]); w.y = cvt_pk_bf16(gelu_tanh(cv[2]) * vv[2], gelu_tanh(cv[3]) * vv[3]);
;             *(u32x2*)(ACT + row * FF + f4) = w;
	v_lshrrev_b32_e32 v2, 1, v85
	v_and_b32_e32 v2, 0x7f, v2
	v_cmp_eq_u32_e32 vcc, 0, v2
	v_and_b32_e32 v3, 1, v85
	v_cmp_eq_u32_e64 s[8:9], 0, v3
	s_nop 1
	s_and_b64 s[8:9], s[8:9], vcc
	s_nop 1
	v_cndmask_b32_e64 v64, v64, 0, vcc
	v_cndmask_b32_e64 v60, v60, 0, s[8:9]
	v_cndmask_b32_e64 v65, v65, 0, vcc
	v_cndmask_b32_e64 v61, v61, 0, s[8:9]
	v_cndmask_b32_e64 v66, v66, 0, vcc
	v_cndmask_b32_e64 v62, v62, 0, s[8:9]
	v_cndmask_b32_e64 v67, v67, 0, vcc
	v_cndmask_b32_e64 v63, v63, 0, s[8:9]
	v_pk_fma_f32 v[66:67], v[66:67], v[74:75], v[70:71]
	v_pk_fma_f32 v[64:65], v[64:65], v[72:73], v[68:69]
	v_pk_fma_f32 v[62:63], v[62:63], v[78:79], v[66:67]
	v_pk_fma_f32 v[60:61], v[60:61], v[76:77], v[64:65]
	v_pk_fma_f32 v[54:55], v[54:55], v[82:83], v[62:63]
	v_pk_fma_f32 v[52:53], v[52:53], v[80:81], v[60:61]
	v_mul_f32_e32 v68, 0x3d922279, v52
	v_mul_f32_e32 v69, 0x3d922279, v53
	v_mul_f32_e32 v70, 0x3d922279, v54
	v_mul_f32_e32 v71, 0x3d922279, v55
	v_fmaak_f32 v68, v52, v68, 0x3fcc422a
	v_fmaak_f32 v69, v53, v69, 0x3fcc422a
	v_fmaak_f32 v70, v54, v70, 0x3fcc422a
	v_fmaak_f32 v71, v55, v71, 0x3fcc422a
	v_mul_f32_e32 v68, v52, v68
	v_mul_f32_e32 v69, v53, v69
	v_mul_f32_e32 v70, v54, v70
	v_mul_f32_e32 v71, v55, v71
	v_mul_f32_e32 v68, 0xbfb8aa3b, v68
	v_mul_f32_e32 v69, 0xbfb8aa3b, v69
	v_mul_f32_e32 v70, 0xbfb8aa3b, v70
	v_mul_f32_e32 v71, 0xbfb8aa3b, v71
	v_exp_f32_e32 v68, v68
	v_exp_f32_e32 v69, v69
	v_exp_f32_e32 v70, v70
	v_exp_f32_e32 v71, v71
	v_add_f32_e32 v68, 1.0, v68
	v_add_f32_e32 v69, 1.0, v69
	v_add_f32_e32 v70, 1.0, v70
	v_add_f32_e32 v71, 1.0, v71
	v_rcp_f32_e32 v68, v68
	v_rcp_f32_e32 v69, v69
	v_rcp_f32_e32 v70, v70
	v_rcp_f32_e32 v71, v71
	v_mul_f32_e32 v52, v52, v68
	v_mul_f32_e32 v53, v53, v69
	v_mul_f32_e32 v54, v54, v70
	v_mul_f32_e32 v55, v55, v71
	v_mul_f32_e32 v52, v56, v52
	v_mul_f32_e32 v53, v57, v53
	v_mul_f32_e32 v54, v58, v54
	v_mul_f32_e32 v55, v59, v55
	v_cvt_pk_bf16_f32 v52, v52, v53
	v_cvt_pk_bf16_f32 v53, v54, v55
	global_store_dwordx2 v84, v[52:53], s[94:95]
	s_waitcnt vmcnt(2)
	v_lshrrev_b32_e32 v2, 1, v121
	v_and_b32_e32 v2, 0x7f, v2
	v_cmp_eq_u32_e32 vcc, 0, v2
	v_and_b32_e32 v3, 1, v121
	v_cmp_eq_u32_e64 s[8:9], 0, v3
	s_nop 1
	s_and_b64 s[8:9], s[8:9], vcc
	s_nop 1
	v_cndmask_b32_e64 v100, v100, 0, vcc
	v_cndmask_b32_e64 v96, v96, 0, s[8:9]
	v_cndmask_b32_e64 v101, v101, 0, vcc
	v_cndmask_b32_e64 v97, v97, 0, s[8:9]
	v_cndmask_b32_e64 v102, v102, 0, vcc
	v_cndmask_b32_e64 v98, v98, 0, s[8:9]
	v_cndmask_b32_e64 v103, v103, 0, vcc
	v_cndmask_b32_e64 v99, v99, 0, s[8:9]
	v_pk_fma_f32 v[102:103], v[102:103], v[110:111], v[106:107]
	v_pk_fma_f32 v[100:101], v[100:101], v[108:109], v[104:105]
	v_pk_fma_f32 v[98:99], v[98:99], v[114:115], v[102:103]
	v_pk_fma_f32 v[96:97], v[96:97], v[112:113], v[100:101]
	v_pk_fma_f32 v[90:91], v[90:91], v[118:119], v[98:99]
	v_pk_fma_f32 v[88:89], v[88:89], v[116:117], v[96:97]
	v_mul_f32_e32 v104, 0x3d922279, v88
	v_mul_f32_e32 v105, 0x3d922279, v89
	v_mul_f32_e32 v106, 0x3d922279, v90
	v_mul_f32_e32 v107, 0x3d922279, v91
	v_fmaak_f32 v104, v88, v104, 0x3fcc422a
	v_fmaak_f32 v105, v89, v105, 0x3fcc422a
	v_fmaak_f32 v106, v90, v106, 0x3fcc422a
	v_fmaak_f32 v107, v91, v107, 0x3fcc422a
	v_mul_f32_e32 v104, v88, v104
	v_mul_f32_e32 v105, v89, v105
	v_mul_f32_e32 v106, v90, v106
	v_mul_f32_e32 v107, v91, v107
	v_mul_f32_e32 v104, 0xbfb8aa3b, v104
	v_mul_f32_e32 v105, 0xbfb8aa3b, v105
	v_mul_f32_e32 v106, 0xbfb8aa3b, v106
	v_mul_f32_e32 v107, 0xbfb8aa3b, v107
	v_exp_f32_e32 v104, v104
	v_exp_f32_e32 v105, v105
	v_exp_f32_e32 v106, v106
	v_exp_f32_e32 v107, v107
	v_add_f32_e32 v104, 1.0, v104
	v_add_f32_e32 v105, 1.0, v105
	v_add_f32_e32 v106, 1.0, v106
	v_add_f32_e32 v107, 1.0, v107
	v_rcp_f32_e32 v104, v104
	v_rcp_f32_e32 v105, v105
	v_rcp_f32_e32 v106, v106
	v_rcp_f32_e32 v107, v107
	v_mul_f32_e32 v88, v88, v104
	v_mul_f32_e32 v89, v89, v105
	v_mul_f32_e32 v90, v90, v106
	v_mul_f32_e32 v91, v91, v107
	v_mul_f32_e32 v88, v92, v88
	v_mul_f32_e32 v89, v93, v89
	v_mul_f32_e32 v90, v94, v90
	v_mul_f32_e32 v91, v95, v91
	v_cvt_pk_bf16_f32 v88, v88, v89
	v_cvt_pk_bf16_f32 v89, v90, v91
	global_store_dwordx2 v120, v[88:89], s[94:95]
	s_or_b64 exec, exec, s[4:5]
	s_waitcnt vmcnt(0)
	s_barrier
	v_readfirstlane_b32 s0, v212
	s_cmp_lg_u32 s0, 64
	s_cbranch_scc1 .Linv_8
	buffer_inv sc1
	s_waitcnt vmcnt(0)
.Linv_8:
	s_and_saveexec_b64 s[0:1], s[72:73]
	s_cbranch_execz .LBB0_1069
	s_add_i32 s4, 0, 0x20020
	v_mov_b32_e32 v0, s4
	s_waitcnt vmcnt(0) expcnt(0) lgkmcnt(0)
	ds_read_b32 v2, v0
	s_add_i32 s4, 0, 0x20024
	v_mov_b32_e32 v0, s4
	ds_read_b32 v0, v0
	s_waitcnt lgkmcnt(1)
	v_cmp_ne_u32_e32 vcc, 0, v2
	s_cbranch_vccnz .LBB0_1033
	v_readlane_b32 s4, v248, 2
	v_readlane_b32 s5, v248, 3
	v_readlane_b32 s6, v248, 1
	s_mul_i32 s29, s5, s6
	s_mul_i32 s29, s29, s4
	s_add_u32 s4, s94, 0x40200
	s_addc_u32 s5, s95, 0
	s_add_u32 s6, s94, 0x40400
	s_addc_u32 s7, s95, 0
	s_add_u32 s8, s94, 0x40500
	s_addc_u32 s9, s95, 0
	s_add_u32 s16, s94, 0x40600
	s_addc_u32 s17, s95, 0
	s_add_u32 s18, s94, 0x40700
	s_addc_u32 s19, s95, 0
	s_add_u32 s20, s94, 0x40800
	s_addc_u32 s21, s95, 0
	s_add_u32 s22, s94, 0x40900
	s_addc_u32 s23, s95, 0
	s_add_u32 s24, s94, 0x40a00
	s_addc_u32 s25, s95, 0
	s_add_u32 s34, s94, 0x40b00
	s_addc_u32 s35, s95, 0
	s_add_u32 s38, s94, 0x40c00
	s_addc_u32 s39, s95, 0
	s_add_u32 s40, s94, 0x40d00
	s_addc_u32 s41, s95, 0
	s_add_u32 s42, s94, 0x40e00
	s_addc_u32 s43, s95, 0
	s_add_u32 s44, s94, 0x40f00
	s_addc_u32 s45, s95, 0
	s_add_u32 s46, s94, 0x41000
	s_addc_u32 s47, s95, 0
	s_add_u32 s48, s94, 0x41100
	s_addc_u32 s49, s95, 0
	s_add_u32 s50, s94, 0x41200
	s_addc_u32 s51, s95, 0
	s_add_u32 s52, s94, 0x41300
	s_addc_u32 s53, s95, 0
	s_mov_b32 s30, 1
	v_mov_b32_e32 v16, 0
	s_branch .LBB0_1021

; __device__ __forceinline__ unsigned xb_add(unsigned* p, unsigned v) { return __hip_atomic_fetch_add(p, v, __ATOMIC_RELAXED, __HIP_MEMORY_SCOPE_AGENT); }
; __device__ __forceinline__ void xcd_barrier(const XcdBarrier& b) {
;     ...
;             __builtin_amdgcn_fence(__ATOMIC_ACQUIRE, "agent");
;             xb_add(&bar[XB_XGEN(b.x)], 1u);
.LBB0_1066:
	s_or_b64 exec, exec, s[6:7]
	s_mov_b64 s[6:7], exec
	v_mbcnt_lo_u32_b32 v0, s6, 0
	v_mbcnt_hi_u32_b32 v0, s7, v0
	v_cmp_eq_u32_e32 vcc, 0, v0
	s_waitcnt vmcnt(0)
	s_and_saveexec_b64 s[8:9], vcc
	s_cbranch_execz .LBB0_1068
	s_bcnt1_i32_b64 s3, s[6:7]
